# NSA sel/window loops: V-fragment LDS reads moved up to after the r=0 scale-fma (9 of 12 halves), on top of bias-read hoist
# baseline (speedup 1.0000x reference)
; template <int MODE>
; __device__ __forceinline__ void nsa_compute(int cur, int buf, int t, int hl, u64 mymask, const bf16x8 (&Qf)[2][2], f32x4 (&O)[4][2], float (&m)[2], float (&l)[2],
;                                             const float (&inv)[2], float* impw, char* lds) {
;     ...
;   for (int s2 = 0; s2 < 2; ++s2) {
;     f32x4 S[2][2] = {};
;     bf16x8 kfr[2][2];
; #pragma unroll
;     for (int ks = 0; ks < 2; ++ks)
; #pragma unroll
;       for (int kk = 0; kk < 2; ++kk) kfr[ks][kk] = *(const bf16x8*)(kt + (32 * s2 + 16 * kk + fr) * 128 + (((ks * 4 + fq) ^ (fr & 7)) << 4));
;     __builtin_amdgcn_s_setprio(1);
; #pragma unroll
;     for (int ks = 0; ks < 2; ++ks)
; #pragma unroll
;       for (int kk = 0; kk < 2; ++kk)
; #pragma unroll
;         for (int r = 0; r < 2; ++r) S[kk][r] = mfma16(kfr[ks][kk], Qf[r][ks], S[kk][r]);
;     __builtin_amdgcn_s_setprio(0);
;     bf16x8 Pf[2];
;     float g1s[2] = {0.f, 0.f}, p3s[2] = {0.f, 0.f};
; #pragma unroll
;     for (int r = 0; r < 2; ++r) {
;       float sv[2][4];
; #pragma unroll
;       for (int kk = 0; kk < 2; ++kk)
; #pragma unroll
;         for (int e = 0; e < 4; ++e) {
;           const int off = 32 * s2 + 16 * kk + e;
;           int idx;
;           if (MODE <= 1) { idx = base - 16 * off; idx = idx > 0 ? idx : 0; } else idx = base - off;
;           sv[kk][e] = S[kk][r][e] * (0.125f * LOG2E) + tb[r * TS + idx];
;         }
;       float pv[2][4];
;       if (MODE == 1) {
; #pragma unroll
;         for (int kk = 0; kk < 2; ++kk)
; #pragma unroll
;           for (int e = 0; e < 4; ++e) pv[kk][e] = __builtin_amdgcn_exp2f(sv[kk][e] - m[r]) * inv[r];
; #pragma unroll
;         for (int kk = 0; kk < 2; ++kk) { g1s[kk] += pv[kk][0] + pv[kk][1] + pv[kk][2] + 0.5f * pv[kk][3]; p3s[kk] += 0.5f * pv[kk][3]; }
;       } else {
;         const float mxa = fmaxf(fmaxf(sv[0][0], sv[0][1]), sv[0][2]), mxb = fmaxf(fmaxf(sv[0][3], sv[1][0]), sv[1][1]);
;         float mx = fmaxf(fmaxf(fmaxf(sv[1][2], sv[1][3]), mxa), mxb);
;         if (MODE == 2) mx = selok ? mx : -__builtin_inff();
;         if (__any(mx > m[r] + 8.0f)) {
;           mx = fmaxf(mx, __shfl_xor(mx, 16)); mx = fmaxf(mx, __shfl_xor(mx, 32));
;           const float mn = fmaxf(m[r], mx), al = __builtin_amdgcn_exp2f(m[r] - mn);
;           m[r] = mn; l[r] *= al;
;           if (MODE != 0) {
; #pragma unroll
.LBB0_361:
	v_mov_b32 v72, v179
	s_lshl_b32 s64, s46, 13
	v_lshrrev_b32_e32 v73, 4, v72
	v_bfe_u32 v80, v72, 4, 2
	v_and_b32_e32 v81, 7, v72
	v_and_b32_e32 v92, 15, v72
	v_lshlrev_b32_e32 v93, 2, v80
	v_bitop3_b32 v72, v73, v81, 3 bitop3:0x6c
	v_bitop3_b32 v80, v80, v81, 4 bitop3:0x36
	v_lshlrev_b32_e32 v90, 7, v92
	v_lshl_or_b32 v91, v72, 4, s64
	v_lshl_or_b32 v100, v80, 4, s64
	v_or_b32_e32 v76, v91, v90
	v_or_b32_e32 v84, v100, v90
	ds_read_b128 v[72:75], v76
	ds_read_b128 v[76:79], v76 offset:2048
	ds_read_b128 v[80:83], v84
	ds_read_b128 v[84:87], v84 offset:2048
	s_mov_b32 s17, s74
	s_mov_b32 s74, s73
	v_sub_u32_e32 v251, v180, v93
	v_lshl_add_u32 v251, v251, 2, v235
	s_lshl_b32 s17, s17, 8
	v_subrev_u32_e32 v250, s17, v251
	v_add_u32_e32 v249, 0xa00, v250
	ds_read2_b32 v[98:99], v250 offset0:63 offset1:64
	ds_read2_b32 v[102:103], v250 offset0:61 offset1:62
	ds_read2_b32 v[168:169], v250 offset0:47 offset1:48
	ds_read2_b32 v[170:171], v250 offset0:45 offset1:46
	ds_read2_b32 v[172:173], v249 offset0:63 offset1:64
	ds_read2_b32 v[174:175], v249 offset0:61 offset1:62
	ds_read2_b32 v[194:195], v249 offset0:47 offset1:48
	ds_read2_b32 v[198:199], v249 offset0:45 offset1:46
	s_setprio 1
	s_waitcnt lgkmcnt(11)
	v_mfma_f32_16x16x32_bf16 v[94:97], v[72:75], v[0:3], 0
	v_mfma_f32_16x16x32_bf16 v[72:75], v[72:75], v[8:11], 0
	s_waitcnt lgkmcnt(10)
	v_mfma_f32_16x16x32_bf16 v[140:143], v[76:79], v[8:11], 0
	v_mfma_f32_16x16x32_bf16 v[136:139], v[76:79], v[0:3], 0
	s_waitcnt lgkmcnt(9)
	v_mfma_f32_16x16x32_bf16 v[94:97], v[80:83], v[4:7], v[94:97]
	v_mfma_f32_16x16x32_bf16 v[76:79], v[80:83], v[12:15], v[72:75]
	s_waitcnt lgkmcnt(8)
	v_mfma_f32_16x16x32_bf16 v[72:75], v[84:87], v[12:15], v[140:143]
	v_mfma_f32_16x16x32_bf16 v[144:147], v[84:87], v[4:7], v[136:139]
	s_setprio 0
	v_sub_u32_e32 v80, v180, v93
	v_lshl_add_u32 v80, v80, 2, v235
	v_subrev_u32_e32 v136, s17, v80
	s_waitcnt lgkmcnt(7)
	v_fmamk_f32 v94, v94, 0x3e38aa3b, v99
	v_fmamk_f32 v86, v95, 0x3e38aa3b, v98
	s_waitcnt lgkmcnt(6)
	v_fmamk_f32 v87, v96, 0x3e38aa3b, v103
	v_fmamk_f32 v84, v97, 0x3e38aa3b, v102
	s_waitcnt lgkmcnt(5)
	v_fmamk_f32 v81, v144, 0x3e38aa3b, v169
	v_fmamk_f32 v80, v145, 0x3e38aa3b, v168
	s_waitcnt lgkmcnt(4)
	v_fmamk_f32 v83, v146, 0x3e38aa3b, v171
	v_fmamk_f32 v82, v147, 0x3e38aa3b, v170
	s_lshl_b32 s17, s46, 9
	v_mul_u32_u24_e32 v101, 0x44, v92
	s_add_i32 s43, s64, s17
	v_lshlrev_b32_e32 v102, 1, v101
	v_lshlrev_b32_e32 v103, 1, v93
	v_add3_u32 v141, s43, v102, v103
	v_add_u32_e32 v137, 0x4000, v141
	v_add_u32_e32 v138, 0x4800, v141
	ds_read2_b64 v[168:171], v137 offset1:4
	ds_read2_b64 v[200:203], v138 offset0:16 offset1:20
	v_add_u32_e32 v139, 0x5000, v141
	v_add_u32_e32 v140, 0x5800, v141
	ds_read2_b64 v[150:153], v139 offset0:32 offset1:36
	ds_read2_b64 v[154:157], v140 offset0:48 offset1:52
	v_max3_f32 v85, v94, v86, v87
	v_max3_f32 v88, v84, v81, v80
	v_max_f32_e32 v89, v83, v82
	v_max3_f32 v85, v89, v85, v88
	v_add_f32_e32 v88, 0x41000000, v192
	v_cmp_gt_f32_e32 vcc, v85, v88
	s_cbranch_vccz .LBB0_363
	ds_bpermute_b32 v88, v233, v85
	v_max_f32_e32 v85, v85, v85
	v_mov_b32_e32 v89, v193
	s_waitcnt lgkmcnt(0)
	v_max_f32_e32 v88, v88, v88
	v_max_f32_e32 v85, v85, v88
	ds_bpermute_b32 v88, v234, v85
	s_waitcnt lgkmcnt(0)
	v_max3_f32 v88, v192, v85, v88
	v_sub_f32_e32 v85, v192, v88
	v_exp_f32_e32 v96, v85
	v_mov_b64_e32 v[192:193], v[88:89]
	v_mul_f32_e32 v190, v190, v96
	v_pk_mul_f32 v[118:119], v[118:119], v[96:97] op_sel_hi:[1,0]
	v_pk_mul_f32 v[116:117], v[116:117], v[96:97] op_sel_hi:[1,0]
	v_pk_mul_f32 v[126:127], v[126:127], v[96:97] op_sel_hi:[1,0]
	v_pk_mul_f32 v[124:125], v[124:125], v[96:97] op_sel_hi:[1,0]
	v_pk_mul_f32 v[130:131], v[130:131], v[96:97] op_sel_hi:[1,0]
	v_pk_mul_f32 v[128:129], v[128:129], v[96:97] op_sel_hi:[1,0]
	v_pk_mul_f32 v[134:135], v[134:135], v[96:97] op_sel_hi:[1,0]
	v_pk_mul_f32 v[132:133], v[132:133], v[96:97] op_sel_hi:[1,0]
	s_branch .LBB0_364

; template <int MODE>
; __device__ __forceinline__ void nsa_compute(int cur, int buf, int t, int hl, u64 mymask, const bf16x8 (&Qf)[2][2], f32x4 (&O)[4][2], float (&m)[2], float (&l)[2],
;                                             const float (&inv)[2], float* impw, char* lds) {
;     ...
;       for (int kk = 0; kk < 2; ++kk)
; #pragma unroll
;         for (int e = 0; e < 4; ++e) {
;           const int off = 32 * s2 + 16 * kk + e;
;           int idx;
;           if (MODE <= 1) { idx = base - 16 * off; idx = idx > 0 ? idx : 0; } else idx = base - off;
;           sv[kk][e] = S[kk][r][e] * (0.125f * LOG2E) + tb[r * TS + idx];
;         }
;       float pv[2][4];
;       if (MODE == 1) {
; #pragma unroll
;         for (int kk = 0; kk < 2; ++kk)
; #pragma unroll
;           for (int e = 0; e < 4; ++e) pv[kk][e] = __builtin_amdgcn_exp2f(sv[kk][e] - m[r]) * inv[r];
; #pragma unroll
;         for (int kk = 0; kk < 2; ++kk) { g1s[kk] += pv[kk][0] + pv[kk][1] + pv[kk][2] + 0.5f * pv[kk][3]; p3s[kk] += 0.5f * pv[kk][3]; }
;       } else {
;         const float mxa = fmaxf(fmaxf(sv[0][0], sv[0][1]), sv[0][2]), mxb = fmaxf(fmaxf(sv[0][3], sv[1][0]), sv[1][1]);
;         float mx = fmaxf(fmaxf(fmaxf(sv[1][2], sv[1][3]), mxa), mxb);
;         if (MODE == 2) mx = selok ? mx : -__builtin_inff();
;         if (__any(mx > m[r] + 8.0f)) {
;           mx = fmaxf(mx, __shfl_xor(mx, 16)); mx = fmaxf(mx, __shfl_xor(mx, 32));
;           const float mn = fmaxf(m[r], mx), al = __builtin_amdgcn_exp2f(m[r] - mn);
;           m[r] = mn; l[r] *= al;
;           if (MODE != 0) {
; #pragma unroll
;             for (int df = 0; df < 4; ++df) O[df][r] *= al;
;           }
;         }
;         const float me = (MODE == 2) ? (selok ? m[r] : __builtin_inff()) : m[r];
;         float ps = 0.f;
; #pragma unroll
;         for (int kk = 0; kk < 2; ++kk)
; #pragma unroll
;           for (int e = 0; e < 4; ++e) { pv[kk][e] = __builtin_amdgcn_exp2f(sv[kk][e] - me); ps += pv[kk][e]; }
;         l[r] += ps;
.LBB0_364:
	v_sub_f32_e32 v85, v94, v88
	v_exp_f32_e32 v85, v85
	v_sub_f32_e32 v86, v86, v88
	v_exp_f32_e32 v86, v86
	v_sub_f32_e32 v87, v87, v88
	v_exp_f32_e32 v87, v87
	v_sub_f32_e32 v84, v84, v88
	v_exp_f32_e32 v84, v84
	v_add_f32_e32 v89, 0, v85
	v_add_f32_e32 v89, v86, v89
	v_add_f32_e32 v89, v87, v89
	v_sub_f32_e32 v81, v81, v88
	v_add_f32_e32 v94, v84, v89
	v_exp_f32_e32 v89, v81
	v_sub_f32_e32 v80, v80, v88
	v_add_f32_e32 v81, v89, v94
	v_exp_f32_e32 v94, v80
	s_nop 0
	v_add_f32_e32 v80, v94, v81
	v_sub_f32_e32 v81, v83, v88
	v_exp_f32_e32 v95, v81
	v_sub_f32_e32 v81, v82, v88
	v_exp_f32_e32 v88, v81
	v_add_f32_e32 v80, v95, v80
	v_add_f32_e32 v80, v88, v80
	v_add_f32_e32 v190, v190, v80
	s_waitcnt lgkmcnt(7)
	v_fmamk_f32 v81, v76, 0x3e38aa3b, v173
	v_fmamk_f32 v80, v77, 0x3e38aa3b, v172
	s_waitcnt lgkmcnt(6)
	v_fmamk_f32 v78, v78, 0x3e38aa3b, v175
	v_fmamk_f32 v82, v79, 0x3e38aa3b, v174
	s_waitcnt lgkmcnt(5)
	v_fmamk_f32 v77, v72, 0x3e38aa3b, v195
	v_fmamk_f32 v76, v73, 0x3e38aa3b, v194
	s_waitcnt lgkmcnt(4)
	v_fmamk_f32 v73, v74, 0x3e38aa3b, v199
	v_fmamk_f32 v72, v75, 0x3e38aa3b, v198
	v_max3_f32 v74, v81, v80, v78
	v_max3_f32 v75, v82, v77, v76
	v_max_f32_e32 v79, v73, v72
	v_max3_f32 v74, v79, v74, v75
	v_add_f32_e32 v75, 0x41000000, v193
	v_cmp_gt_f32_e32 vcc, v74, v75
	s_cbranch_vccz .LBB0_366
	ds_bpermute_b32 v75, v233, v74
	v_max_f32_e32 v74, v74, v74
	s_waitcnt lgkmcnt(0)
	v_max_f32_e32 v75, v75, v75
	v_max_f32_e32 v74, v74, v75
	ds_bpermute_b32 v75, v234, v74
	s_waitcnt lgkmcnt(0)
	v_max3_f32 v74, v193, v74, v75
	v_sub_f32_e32 v75, v193, v74
	v_exp_f32_e32 v96, v75
	v_mov_b32_e32 v193, v74
	v_mul_f32_e32 v191, v191, v96
	v_pk_mul_f32 v[106:107], v[106:107], v[96:97] op_sel_hi:[1,0]
	v_pk_mul_f32 v[104:105], v[104:105], v[96:97] op_sel_hi:[1,0]
	v_pk_mul_f32 v[110:111], v[110:111], v[96:97] op_sel_hi:[1,0]
	v_pk_mul_f32 v[108:109], v[108:109], v[96:97] op_sel_hi:[1,0]
	v_pk_mul_f32 v[114:115], v[114:115], v[96:97] op_sel_hi:[1,0]
	v_pk_mul_f32 v[112:113], v[112:113], v[96:97] op_sel_hi:[1,0]
	v_pk_mul_f32 v[122:123], v[122:123], v[96:97] op_sel_hi:[1,0]
	v_pk_mul_f32 v[120:121], v[120:121], v[96:97] op_sel_hi:[1,0]
	s_branch .LBB0_367

; template <int MODE>
; __device__ __forceinline__ void nsa_compute(int cur, int buf, int t, int hl, u64 mymask, const bf16x8 (&Qf)[2][2], f32x4 (&O)[4][2], float (&m)[2], float (&l)[2],
;                                             const float (&inv)[2], float* impw, char* lds) {
;     ...
; #pragma unroll
;     for (int ks = 0; ks < 2; ++ks)
; #pragma unroll
;       for (int kk = 0; kk < 2; ++kk) kfr[ks][kk] = *(const bf16x8*)(kt + (32 * s2 + 16 * kk + fr) * 128 + (((ks * 4 + fq) ^ (fr & 7)) << 4));
;     __builtin_amdgcn_s_setprio(1);
; #pragma unroll
;     for (int ks = 0; ks < 2; ++ks)
; #pragma unroll
;       for (int kk = 0; kk < 2; ++kk)
; #pragma unroll
;         for (int r = 0; r < 2; ++r) S[kk][r] = mfma16(kfr[ks][kk], Qf[r][ks], S[kk][r]);
;     __builtin_amdgcn_s_setprio(0);
;     bf16x8 Pf[2];
;     float g1s[2] = {0.f, 0.f}, p3s[2] = {0.f, 0.f};
; #pragma unroll
;     for (int r = 0; r < 2; ++r) {
;       float sv[2][4];
; #pragma unroll
;       for (int kk = 0; kk < 2; ++kk)
; #pragma unroll
;         for (int e = 0; e < 4; ++e) {
;     ...
;         const float me = (MODE == 2) ? (selok ? m[r] : __builtin_inff()) : m[r];
;         float ps = 0.f;
; #pragma unroll
;         for (int kk = 0; kk < 2; ++kk)
; #pragma unroll
;           for (int e = 0; e < 4; ++e) { pv[kk][e] = __builtin_amdgcn_exp2f(sv[kk][e] - me); ps += pv[kk][e]; }
;         l[r] += ps;
;       }
;       if (MODE != 0) {
;         const unsigned w0 = pk2(pv[0][0], pv[0][1]), w1 = pk2(pv[0][2], pv[0][3]), w2 = pk2(pv[1][0], pv[1][1]), w3 = pk2(pv[1][2], pv[1][3]);
;         u32x4 pw; pw.x = w0; pw.y = w1; pw.z = w2; pw.w = w3;
;         Pf[r] = __builtin_bit_cast(bf16x8, pw);
;       }
;     }
;     if (MODE != 0) {
;       bf16x8 vfr[4];
; #pragma unroll
;       for (int df = 0; df < 4; ++df) {
;         const bf16x4 va = *(const bf16x4*)(vt + (df * 16 + fr) * 68 + 32 * s2 + 4 * fq);
;         const bf16x4 vb = *(const bf16x4*)(vt + (df * 16 + fr) * 68 + 32 * s2 + 16 + 4 * fq);
;         bf16x8 vf; vf[0] = va[0]; vf[1] = va[1]; vf[2] = va[2]; vf[3] = va[3]; vf[4] = vb[0]; vf[5] = vb[1]; vf[6] = vb[2]; vf[7] = vb[3];
;         vfr[df] = vf;
;       }
;       __builtin_amdgcn_s_setprio(1);
; #pragma unroll
;       for (int df = 0; df < 4; ++df)
; #pragma unroll
;         for (int r = 0; r < 2; ++r) O[df][r] = mfma16(vfr[df], Pf[r], O[df][r]);
;       __builtin_amdgcn_s_setprio(0);
;     }
.LBB0_367:
	v_sub_f32_e32 v75, v81, v74
	v_exp_f32_e32 v75, v75
	v_sub_f32_e32 v80, v80, v74
	v_exp_f32_e32 v80, v80
	v_sub_f32_e32 v78, v78, v74
	v_exp_f32_e32 v78, v78
	v_sub_f32_e32 v81, v82, v74
	v_exp_f32_e32 v81, v81
	v_sub_f32_e32 v77, v77, v74
	v_add_f32_e32 v79, 0, v75
	v_exp_f32_e32 v77, v77
	v_sub_f32_e32 v76, v76, v74
	v_add_f32_e32 v79, v80, v79
	v_exp_f32_e32 v76, v76
	v_sub_f32_e32 v73, v73, v74
	v_add_f32_e32 v79, v78, v79
	v_exp_f32_e32 v73, v73
	v_sub_f32_e32 v72, v72, v74
	v_add_f32_e32 v79, v81, v79
	v_exp_f32_e32 v72, v72
	v_add_f32_e32 v79, v77, v79
	v_add_f32_e32 v79, v76, v79
	v_add_f32_e32 v79, v73, v79
	v_add_f32_e32 v74, v72, v79
	v_cvt_pk_bf16_f32 v149, v73, v72
	v_cvt_pk_bf16_f32 v146, v75, v80
	v_add_f32_e32 v191, v191, v74
	v_cvt_pk_bf16_f32 v147, v78, v81
	v_cvt_pk_bf16_f32 v148, v77, v76
	v_cvt_pk_bf16_f32 v142, v85, v86
	v_cvt_pk_bf16_f32 v143, v87, v84
	v_cvt_pk_bf16_f32 v144, v89, v94
	v_cvt_pk_bf16_f32 v145, v95, v88
	s_setprio 1
	s_waitcnt lgkmcnt(3)
	v_mfma_f32_16x16x32_bf16 v[84:87], v[168:171], v[142:145], v[116:119]
	v_mfma_f32_16x16x32_bf16 v[96:99], v[168:171], v[146:149], v[104:107]
	s_waitcnt lgkmcnt(2)
	v_mfma_f32_16x16x32_bf16 v[80:83], v[200:203], v[142:145], v[124:127]
	v_mfma_f32_16x16x32_bf16 v[92:95], v[200:203], v[146:149], v[108:111]
	s_waitcnt lgkmcnt(1)
	v_mfma_f32_16x16x32_bf16 v[76:79], v[150:153], v[142:145], v[128:131]
	v_mfma_f32_16x16x32_bf16 v[108:111], v[150:153], v[146:149], v[112:115]
	s_waitcnt lgkmcnt(0)
	v_mfma_f32_16x16x32_bf16 v[72:75], v[154:157], v[142:145], v[132:135]
	v_mfma_f32_16x16x32_bf16 v[104:107], v[154:157], v[146:149], v[120:123]
	s_setprio 0
	v_add_u32_e32 v88, v91, v90
	v_add_u32_e32 v100, v100, v90
	ds_read_b128 v[112:115], v88 offset:4096
	ds_read_b128 v[116:119], v88 offset:6144
	ds_read_b128 v[88:91], v100 offset:4096
	ds_read_b128 v[120:123], v100 offset:6144
	v_add_u32_e32 v251, 0xa00, v136
	ds_read2_b32 v[168:169], v136 offset0:31 offset1:32
	ds_read2_b32 v[170:171], v136 offset0:29 offset1:30
	ds_read2_b32 v[172:173], v136 offset0:15 offset1:16
	ds_read2_b32 v[174:175], v136 offset0:13 offset1:14
	ds_read2_b32 v[198:199], v251 offset0:31 offset1:32
	ds_read2_b32 v[200:201], v251 offset0:29 offset1:30
	ds_read2_b32 v[202:203], v251 offset0:15 offset1:16
	ds_read2_b32 v[204:205], v251 offset0:13 offset1:14
	s_setprio 1
	s_waitcnt lgkmcnt(11)
	v_mfma_f32_16x16x32_bf16 v[100:103], v[112:115], v[0:3], 0
	v_mfma_f32_16x16x32_bf16 v[112:115], v[112:115], v[8:11], 0
	s_waitcnt lgkmcnt(10)
	v_mfma_f32_16x16x32_bf16 v[124:127], v[116:119], v[0:3], 0
	v_mfma_f32_16x16x32_bf16 v[116:119], v[116:119], v[8:11], 0
	s_waitcnt lgkmcnt(9)
	v_mfma_f32_16x16x32_bf16 v[128:131], v[88:91], v[4:7], v[100:103]
	v_mfma_f32_16x16x32_bf16 v[100:103], v[88:91], v[12:15], v[112:115]
	s_waitcnt lgkmcnt(8)
	v_mfma_f32_16x16x32_bf16 v[88:91], v[120:123], v[12:15], v[116:119]
	v_mfma_f32_16x16x32_bf16 v[124:127], v[120:123], v[4:7], v[124:127]
	s_setprio 0
	s_nop 0
	s_waitcnt lgkmcnt(7)
	s_nop 0
	v_fmamk_f32 v123, v128, 0x3e38aa3b, v169
	v_fmamk_f32 v118, v129, 0x3e38aa3b, v168
	s_waitcnt lgkmcnt(6)
	v_fmamk_f32 v122, v130, 0x3e38aa3b, v171
	v_fmamk_f32 v116, v131, 0x3e38aa3b, v170
	s_waitcnt lgkmcnt(5)
	v_fmamk_f32 v119, v124, 0x3e38aa3b, v173
	v_fmamk_f32 v114, v125, 0x3e38aa3b, v172
	s_waitcnt lgkmcnt(4)
	v_fmamk_f32 v113, v126, 0x3e38aa3b, v175
	v_fmamk_f32 v112, v127, 0x3e38aa3b, v174
	ds_read2_b64 v[168:171], v137 offset0:8 offset1:12
	ds_read2_b64 v[126:129], v138 offset0:24 offset1:28
	ds_read2_b64 v[130:133], v139 offset0:40 offset1:44
	ds_read2_b64 v[134:137], v140 offset0:56 offset1:60
	v_max3_f32 v115, v123, v118, v122
	v_max3_f32 v117, v116, v119, v114
	v_max_f32_e32 v120, v113, v112
	v_max3_f32 v115, v120, v115, v117
	v_add_f32_e32 v117, 0x41000000, v192
	v_cmp_gt_f32_e32 vcc, v115, v117
	s_cbranch_vccz .LBB0_369
	ds_bpermute_b32 v117, v233, v115
	v_max_f32_e32 v115, v115, v115
	v_mov_b32_e32 v121, v193
	s_waitcnt lgkmcnt(0)
	v_max_f32_e32 v117, v117, v117
	v_max_f32_e32 v115, v115, v117
	ds_bpermute_b32 v117, v234, v115
	s_waitcnt lgkmcnt(0)
	v_max3_f32 v120, v192, v115, v117
	v_sub_f32_e32 v115, v192, v120
	v_exp_f32_e32 v124, v115
	v_mov_b64_e32 v[192:193], v[120:121]
	v_mul_f32_e32 v190, v190, v124
	v_pk_mul_f32 v[86:87], v[86:87], v[124:125] op_sel_hi:[1,0]
	v_pk_mul_f32 v[84:85], v[84:85], v[124:125] op_sel_hi:[1,0]
	v_pk_mul_f32 v[82:83], v[82:83], v[124:125] op_sel_hi:[1,0]
	v_pk_mul_f32 v[80:81], v[80:81], v[124:125] op_sel_hi:[1,0]
	v_pk_mul_f32 v[78:79], v[78:79], v[124:125] op_sel_hi:[1,0]
	v_pk_mul_f32 v[76:77], v[76:77], v[124:125] op_sel_hi:[1,0]
	v_pk_mul_f32 v[74:75], v[74:75], v[124:125] op_sel_hi:[1,0]
	v_pk_mul_f32 v[72:73], v[72:73], v[124:125] op_sel_hi:[1,0]
	s_branch .LBB0_370

; template <int MODE>
; __device__ __forceinline__ void nsa_compute(int cur, int buf, int t, int hl, u64 mymask, const bf16x8 (&Qf)[2][2], f32x4 (&O)[4][2], float (&m)[2], float (&l)[2],
;                                             const float (&inv)[2], float* impw, char* lds) {
;     ...
;       for (int kk = 0; kk < 2; ++kk)
; #pragma unroll
;         for (int e = 0; e < 4; ++e) {
;           const int off = 32 * s2 + 16 * kk + e;
;           int idx;
;           if (MODE <= 1) { idx = base - 16 * off; idx = idx > 0 ? idx : 0; } else idx = base - off;
;           sv[kk][e] = S[kk][r][e] * (0.125f * LOG2E) + tb[r * TS + idx];
;         }
;       float pv[2][4];
;       if (MODE == 1) {
; #pragma unroll
;         for (int kk = 0; kk < 2; ++kk)
; #pragma unroll
;           for (int e = 0; e < 4; ++e) pv[kk][e] = __builtin_amdgcn_exp2f(sv[kk][e] - m[r]) * inv[r];
; #pragma unroll
;         for (int kk = 0; kk < 2; ++kk) { g1s[kk] += pv[kk][0] + pv[kk][1] + pv[kk][2] + 0.5f * pv[kk][3]; p3s[kk] += 0.5f * pv[kk][3]; }
;       } else {
;         const float mxa = fmaxf(fmaxf(sv[0][0], sv[0][1]), sv[0][2]), mxb = fmaxf(fmaxf(sv[0][3], sv[1][0]), sv[1][1]);
;         float mx = fmaxf(fmaxf(fmaxf(sv[1][2], sv[1][3]), mxa), mxb);
;         if (MODE == 2) mx = selok ? mx : -__builtin_inff();
;         if (__any(mx > m[r] + 8.0f)) {
;           mx = fmaxf(mx, __shfl_xor(mx, 16)); mx = fmaxf(mx, __shfl_xor(mx, 32));
;           const float mn = fmaxf(m[r], mx), al = __builtin_amdgcn_exp2f(m[r] - mn);
;           m[r] = mn; l[r] *= al;
;           if (MODE != 0) {
; #pragma unroll
;             for (int df = 0; df < 4; ++df) O[df][r] *= al;
;           }
;         }
;         const float me = (MODE == 2) ? (selok ? m[r] : __builtin_inff()) : m[r];
;         float ps = 0.f;
; #pragma unroll
;         for (int kk = 0; kk < 2; ++kk)
; #pragma unroll
;           for (int e = 0; e < 4; ++e) { pv[kk][e] = __builtin_amdgcn_exp2f(sv[kk][e] - me); ps += pv[kk][e]; }
;         l[r] += ps;
.LBB0_370:
	v_sub_f32_e32 v115, v123, v120
	v_exp_f32_e32 v115, v115
	v_sub_f32_e32 v117, v118, v120
	v_exp_f32_e32 v117, v117
	v_sub_f32_e32 v118, v122, v120
	v_exp_f32_e32 v118, v118
	v_sub_f32_e32 v116, v116, v120
	v_exp_f32_e32 v116, v116
	v_sub_f32_e32 v119, v119, v120
	v_add_f32_e32 v121, 0, v115
	v_exp_f32_e32 v119, v119
	v_sub_f32_e32 v114, v114, v120
	v_add_f32_e32 v121, v117, v121
	v_exp_f32_e32 v114, v114
	v_add_f32_e32 v121, v118, v121
	v_add_f32_e32 v121, v116, v121
	v_add_f32_e32 v121, v119, v121
	v_sub_f32_e32 v113, v113, v120
	v_add_f32_e32 v122, v114, v121
	v_exp_f32_e32 v121, v113
	v_sub_f32_e32 v112, v112, v120
	v_exp_f32_e32 v120, v112
	v_add_f32_e32 v113, v121, v122
	v_add_f32_e32 v112, v120, v113
	v_add_f32_e32 v190, v190, v112
	s_waitcnt lgkmcnt(7)
	v_fmamk_f32 v113, v100, 0x3e38aa3b, v199
	v_fmamk_f32 v112, v101, 0x3e38aa3b, v198
	s_waitcnt lgkmcnt(6)
	v_fmamk_f32 v101, v102, 0x3e38aa3b, v201
	v_fmamk_f32 v100, v103, 0x3e38aa3b, v200
	s_waitcnt lgkmcnt(5)
	v_fmamk_f32 v103, v88, 0x3e38aa3b, v203
	v_fmamk_f32 v102, v89, 0x3e38aa3b, v202
	s_waitcnt lgkmcnt(4)
	v_fmamk_f32 v89, v90, 0x3e38aa3b, v205
	v_fmamk_f32 v88, v91, 0x3e38aa3b, v204
	v_max3_f32 v90, v113, v112, v101
	v_max3_f32 v91, v100, v103, v102
	v_max_f32_e32 v122, v89, v88
	v_max3_f32 v90, v122, v90, v91
	v_add_f32_e32 v91, 0x41000000, v193
	v_cmp_gt_f32_e32 vcc, v90, v91
	s_cbranch_vccz .LBB0_372
	ds_bpermute_b32 v91, v233, v90
	v_max_f32_e32 v90, v90, v90
	s_waitcnt lgkmcnt(0)
	v_max_f32_e32 v91, v91, v91
	v_max_f32_e32 v90, v90, v91
	ds_bpermute_b32 v91, v234, v90
	s_waitcnt lgkmcnt(0)
	v_max3_f32 v90, v193, v90, v91
	v_sub_f32_e32 v91, v193, v90
	v_exp_f32_e32 v122, v91
	v_mov_b32_e32 v193, v90
	v_mul_f32_e32 v191, v191, v122
	v_pk_mul_f32 v[98:99], v[98:99], v[122:123] op_sel_hi:[1,0]
	v_pk_mul_f32 v[96:97], v[96:97], v[122:123] op_sel_hi:[1,0]
	v_pk_mul_f32 v[94:95], v[94:95], v[122:123] op_sel_hi:[1,0]
	v_pk_mul_f32 v[92:93], v[92:93], v[122:123] op_sel_hi:[1,0]
	v_pk_mul_f32 v[110:111], v[110:111], v[122:123] op_sel_hi:[1,0]
	v_pk_mul_f32 v[108:109], v[108:109], v[122:123] op_sel_hi:[1,0]
	v_pk_mul_f32 v[106:107], v[106:107], v[122:123] op_sel_hi:[1,0]
	v_pk_mul_f32 v[104:105], v[104:105], v[122:123] op_sel_hi:[1,0]
	v_mov_b64_e32 v[194:195], v[190:191]
	s_branch .LBB0_373

; #define TIDX opaque_tid()
; __device__ __forceinline__ unsigned pk2(float lo, float hi) { const f32x2v v = {lo, hi}; const bf16x2v r = __builtin_convertvector(v, bf16x2v); return __builtin_bit_cast(unsigned, r); }
; __device__ __forceinline__ void kv_lwrite(const KVRegs& r, char* lds, int buf) {
;   const int tid = TIDX, row = tid >> 3, cq = tid & 7;
;   char* kt = lds + NSA_KT + buf * 8192 + row * 128;
;   *(u32x4*)(kt + ((cq ^ (row & 7)) << 4)) = r.k0;
;   bf16_t* vt = (bf16_t*)(lds + NSA_VT + buf * 8704) + (cq * 8) * 68 + row;
; #pragma unroll
;   for (int i = 0; i < 4; ++i) { vt[(2 * i) * 68] = (bf16_t)(r.v0[i] & 0xffffu); vt[(2 * i + 1) * 68] = (bf16_t)(r.v0[i] >> 16); }
; }
; template <int MODE>
; __device__ __forceinline__ void nsa_compute(int cur, int buf, int t, int hl, u64 mymask, const bf16x8 (&Qf)[2][2], f32x4 (&O)[4][2], float (&m)[2], float (&l)[2],
;                                             const float (&inv)[2], float* impw, char* lds) {
;     ...
;         const float me = (MODE == 2) ? (selok ? m[r] : __builtin_inff()) : m[r];
;         float ps = 0.f;
; #pragma unroll
;         for (int kk = 0; kk < 2; ++kk)
; #pragma unroll
;           for (int e = 0; e < 4; ++e) { pv[kk][e] = __builtin_amdgcn_exp2f(sv[kk][e] - me); ps += pv[kk][e]; }
;         l[r] += ps;
;       }
;       if (MODE != 0) {
;         const unsigned w0 = pk2(pv[0][0], pv[0][1]), w1 = pk2(pv[0][2], pv[0][3]), w2 = pk2(pv[1][0], pv[1][1]), w3 = pk2(pv[1][2], pv[1][3]);
;         u32x4 pw; pw.x = w0; pw.y = w1; pw.z = w2; pw.w = w3;
;         Pf[r] = __builtin_bit_cast(bf16x8, pw);
;       }
;     }
;     if (MODE != 0) {
;       bf16x8 vfr[4];
; #pragma unroll
;       for (int df = 0; df < 4; ++df) {
;         const bf16x4 va = *(const bf16x4*)(vt + (df * 16 + fr) * 68 + 32 * s2 + 4 * fq);
;         const bf16x4 vb = *(const bf16x4*)(vt + (df * 16 + fr) * 68 + 32 * s2 + 16 + 4 * fq);
;         bf16x8 vf; vf[0] = va[0]; vf[1] = va[1]; vf[2] = va[2]; vf[3] = va[3]; vf[4] = vb[0]; vf[5] = vb[1]; vf[6] = vb[2]; vf[7] = vb[3];
;         vfr[df] = vf;
;       }
;       __builtin_amdgcn_s_setprio(1);
; #pragma unroll
;       for (int df = 0; df < 4; ++df)
; #pragma unroll
;         for (int r = 0; r < 2; ++r) O[df][r] = mfma16(vfr[df], Pf[r], O[df][r]);
;       __builtin_amdgcn_s_setprio(0);
.LBB0_373:
	v_sub_f32_e32 v91, v113, v90
	v_exp_f32_e32 v113, v91
	v_sub_f32_e32 v91, v112, v90
	v_exp_f32_e32 v112, v91
	v_sub_f32_e32 v91, v101, v90
	v_cvt_pk_bf16_f32 v124, v119, v114
	v_exp_f32_e32 v114, v91
	v_sub_f32_e32 v91, v100, v90
	v_cvt_pk_bf16_f32 v122, v115, v117
	v_exp_f32_e32 v115, v91
	v_sub_f32_e32 v91, v103, v90
	v_cvt_pk_bf16_f32 v123, v118, v116
	v_exp_f32_e32 v116, v91
	v_sub_f32_e32 v91, v102, v90
	v_sub_f32_e32 v89, v89, v90
	v_sub_f32_e32 v88, v88, v90
	v_exp_f32_e32 v117, v91
	v_exp_f32_e32 v118, v89
	v_exp_f32_e32 v119, v88
	v_cvt_pk_bf16_f32 v125, v121, v120
	v_cvt_pk_bf16_f32 v138, v113, v112
	v_cvt_pk_bf16_f32 v139, v114, v115
	v_cvt_pk_bf16_f32 v140, v116, v117
	v_cvt_pk_bf16_f32 v141, v118, v119
	s_setprio 1
	s_waitcnt lgkmcnt(3)
	v_mfma_f32_16x16x32_bf16 v[88:91], v[168:171], v[122:125], v[84:87]
	v_mfma_f32_16x16x32_bf16 v[96:99], v[168:171], v[138:141], v[96:99]
	s_waitcnt lgkmcnt(2)
	v_mfma_f32_16x16x32_bf16 v[100:103], v[126:129], v[122:125], v[80:83]
	v_mfma_f32_16x16x32_bf16 v[84:87], v[126:129], v[138:141], v[92:95]
	s_waitcnt lgkmcnt(1)
	v_mfma_f32_16x16x32_bf16 v[92:95], v[130:133], v[122:125], v[76:79]
	v_mfma_f32_16x16x32_bf16 v[76:79], v[130:133], v[138:141], v[108:111]
	s_waitcnt lgkmcnt(0)
	v_mfma_f32_16x16x32_bf16 v[80:83], v[134:137], v[122:125], v[72:75]
	v_mfma_f32_16x16x32_bf16 v[72:75], v[134:137], v[138:141], v[104:107]
	s_setprio 0
	s_xor_b32 s46, s46, 1
	s_cmp_lt_i32 s16, 0
	s_cbranch_scc1 .LBB0_375
	v_mov_b32 v104, v179
	s_lshl_b32 s17, s46, 13
	v_ashrrev_i32_e32 v105, 3, v104
	v_xor_b32_e32 v107, v105, v104
	v_lshl_add_u32 v106, v105, 7, s17
	v_lshlrev_b32_e32 v107, 4, v107
	s_movk_i32 s30, 0x70
	v_lshlrev_b32_e32 v104, 3, v104
	v_and_or_b32 v106, v107, s30, v106
	s_lshl_b32 s30, s46, 9
	v_and_b32_e32 v104, 56, v104
	s_add_i32 s17, s17, s30
	v_mul_u32_u24_e32 v104, 0x88, v104
	v_lshlrev_b32_e32 v105, 1, v105
	v_add3_u32 v104, s17, v104, v105
	s_waitcnt vmcnt(1)
	ds_write_b128 v106, v[56:59]
	s_waitcnt vmcnt(0)
	ds_write_b16 v104, v60 offset:16384
	ds_write_b16_d16_hi v104, v60 offset:16520
	ds_write_b16 v104, v61 offset:16656
	ds_write_b16_d16_hi v104, v61 offset:16792
	ds_write_b16 v104, v62 offset:16928
	ds_write_b16_d16_hi v104, v62 offset:17064
	ds_write_b16 v104, v63 offset:17200
	ds_write_b16_d16_hi v104, v63 offset:17336

; template <int MODE>
; __device__ __forceinline__ void nsa_compute(int cur, int buf, int t, int hl, u64 mymask, const bf16x8 (&Qf)[2][2], f32x4 (&O)[4][2], float (&m)[2], float (&l)[2],
;                                             const float (&inv)[2], float* impw, char* lds) {
;     ...
; #pragma unroll
;     for (int ks = 0; ks < 2; ++ks)
; #pragma unroll
;       for (int kk = 0; kk < 2; ++kk) kfr[ks][kk] = *(const bf16x8*)(kt + (32 * s2 + 16 * kk + fr) * 128 + (((ks * 4 + fq) ^ (fr & 7)) << 4));
;     __builtin_amdgcn_s_setprio(1);
; #pragma unroll
;     for (int ks = 0; ks < 2; ++ks)
; #pragma unroll
;       for (int kk = 0; kk < 2; ++kk)
; #pragma unroll
;         for (int r = 0; r < 2; ++r) S[kk][r] = mfma16(kfr[ks][kk], Qf[r][ks], S[kk][r]);
;     __builtin_amdgcn_s_setprio(0);
;     bf16x8 Pf[2];
;     float g1s[2] = {0.f, 0.f}, p3s[2] = {0.f, 0.f};
; #pragma unroll
;     for (int r = 0; r < 2; ++r) {
;       float sv[2][4];
; #pragma unroll
;       for (int kk = 0; kk < 2; ++kk)
; #pragma unroll
;         for (int e = 0; e < 4; ++e) {
;     ...
;         const float me = (MODE == 2) ? (selok ? m[r] : __builtin_inff()) : m[r];
;         float ps = 0.f;
; #pragma unroll
;         for (int kk = 0; kk < 2; ++kk)
; #pragma unroll
;           for (int e = 0; e < 4; ++e) { pv[kk][e] = __builtin_amdgcn_exp2f(sv[kk][e] - me); ps += pv[kk][e]; }
;         l[r] += ps;
;       }
;       if (MODE != 0) {
;         const unsigned w0 = pk2(pv[0][0], pv[0][1]), w1 = pk2(pv[0][2], pv[0][3]), w2 = pk2(pv[1][0], pv[1][1]), w3 = pk2(pv[1][2], pv[1][3]);
;         u32x4 pw; pw.x = w0; pw.y = w1; pw.z = w2; pw.w = w3;
;         Pf[r] = __builtin_bit_cast(bf16x8, pw);
;       }
;     }
;     if (MODE != 0) {
;       bf16x8 vfr[4];
; #pragma unroll
;       for (int df = 0; df < 4; ++df) {
;         const bf16x4 va = *(const bf16x4*)(vt + (df * 16 + fr) * 68 + 32 * s2 + 4 * fq);
;         const bf16x4 vb = *(const bf16x4*)(vt + (df * 16 + fr) * 68 + 32 * s2 + 16 + 4 * fq);
;         bf16x8 vf; vf[0] = va[0]; vf[1] = va[1]; vf[2] = va[2]; vf[3] = va[3]; vf[4] = vb[0]; vf[5] = vb[1]; vf[6] = vb[2]; vf[7] = vb[3];
;         vfr[df] = vf;
;       }
;       __builtin_amdgcn_s_setprio(1);
; #pragma unroll
;       for (int df = 0; df < 4; ++df)
; #pragma unroll
;         for (int r = 0; r < 2; ++r) O[df][r] = mfma16(vfr[df], Pf[r], O[df][r]);
;       __builtin_amdgcn_s_setprio(0);
;     }
.LBB0_385:
	v_sub_f32_e32 v119, v135, v118
	v_exp_f32_e32 v119, v119
	v_sub_f32_e32 v134, v134, v118
	v_exp_f32_e32 v134, v134
	v_sub_f32_e32 v145, v145, v118
	v_exp_f32_e32 v145, v145
	v_sub_f32_e32 v144, v144, v118
	v_exp_f32_e32 v144, v144
	v_sub_f32_e32 v133, v133, v118
	v_add_f32_e32 v135, 0, v119
	v_exp_f32_e32 v133, v133
	v_sub_f32_e32 v132, v132, v118
	v_add_f32_e32 v135, v134, v135
	v_exp_f32_e32 v132, v132
	v_sub_f32_e32 v117, v117, v118
	v_add_f32_e32 v135, v145, v135
	v_exp_f32_e32 v117, v117
	v_sub_f32_e32 v116, v116, v118
	v_add_f32_e32 v135, v144, v135
	v_exp_f32_e32 v116, v116
	v_add_f32_e32 v135, v133, v135
	v_add_f32_e32 v135, v132, v135
	v_add_f32_e32 v135, v117, v135
	s_lshl_b32 s16, s46, 9
	v_add_f32_e32 v118, v116, v135
	v_cvt_pk_bf16_f32 v167, v117, v116
	v_mul_u32_u24_e32 v116, 0x44, v149
	s_add_i32 s72, s71, s16
	v_lshlrev_b32_e32 v116, 1, v116
	v_lshlrev_b32_e32 v117, 1, v150
	v_add3_u32 v116, s72, v116, v117
	v_cvt_pk_bf16_f32 v161, v153, v155
	v_cvt_pk_bf16_f32 v162, v156, v157
	v_add_u32_e32 v155, 0x4000, v116
	v_add_u32_e32 v156, 0x4800, v116
	v_cvt_pk_bf16_f32 v160, v151, v152
	v_cvt_pk_bf16_f32 v163, v158, v159
	v_cvt_pk_bf16_f32 v164, v119, v134
	v_cvt_pk_bf16_f32 v166, v133, v132
	ds_read2_b64 v[132:135], v155 offset1:4
	ds_read2_b64 v[150:153], v156 offset0:16 offset1:20
	v_add_u32_e32 v157, 0x5000, v116
	v_add_u32_e32 v158, 0x5800, v116
	ds_read2_b64 v[168:171], v157 offset0:32 offset1:36
	ds_read2_b64 v[172:175], v158 offset0:48 offset1:52
	v_add_f32_e32 v197, v197, v118
	v_cvt_pk_bf16_f32 v165, v145, v144
	s_setprio 1
	s_waitcnt lgkmcnt(3)
	v_mfma_f32_16x16x32_bf16 v[116:119], v[132:135], v[160:163], v[112:115]
	v_mfma_f32_16x16x32_bf16 v[132:135], v[132:135], v[164:167], v[124:127]
	s_waitcnt lgkmcnt(2)
	v_mfma_f32_16x16x32_bf16 v[112:115], v[150:153], v[160:163], v[104:107]
	v_mfma_f32_16x16x32_bf16 v[128:131], v[150:153], v[164:167], v[128:131]
	s_waitcnt lgkmcnt(1)
	v_mfma_f32_16x16x32_bf16 v[108:111], v[168:171], v[160:163], v[108:111]
	v_mfma_f32_16x16x32_bf16 v[124:127], v[168:171], v[164:167], v[136:139]
	s_waitcnt lgkmcnt(0)
	v_mfma_f32_16x16x32_bf16 v[104:107], v[172:175], v[160:163], v[120:123]
	v_mfma_f32_16x16x32_bf16 v[120:123], v[172:175], v[164:167], v[140:143]
	s_setprio 0
	s_nop 1
	v_add_u32_e32 v140, v147, v146
	v_add_u32_e32 v148, v148, v146
	ds_read_b128 v[136:139], v140 offset:4096
	ds_read_b128 v[140:143], v140 offset:6144
	ds_read_b128 v[144:147], v148 offset:4096
	ds_read_b128 v[148:151], v148 offset:6144
	v_add_u32_e32 v251, 0xa00, v154
	ds_read2_b32 v[202:203], v154 offset0:31 offset1:32
	ds_read2_b32 v[204:205], v154 offset0:29 offset1:30
	ds_read2_b32 v[206:207], v154 offset0:15 offset1:16
	ds_read2_b32 v[208:209], v154 offset0:13 offset1:14
	ds_read2_b32 v[210:211], v251 offset0:31 offset1:32
	ds_read2_b32 v[236:237], v251 offset0:29 offset1:30
	ds_read2_b32 v[238:239], v251 offset0:15 offset1:16
	ds_read2_b32 v[240:241], v251 offset0:13 offset1:14
	s_setprio 1
	s_waitcnt lgkmcnt(11)
	v_mfma_f32_16x16x32_bf16 v[160:163], v[136:139], v[0:3], 0
	v_mfma_f32_16x16x32_bf16 v[136:139], v[136:139], v[8:11], 0
	s_waitcnt lgkmcnt(10)
	v_mfma_f32_16x16x32_bf16 v[168:171], v[140:143], v[8:11], 0
	v_mfma_f32_16x16x32_bf16 v[164:167], v[140:143], v[0:3], 0
	s_waitcnt lgkmcnt(9)
	v_mfma_f32_16x16x32_bf16 v[160:163], v[144:147], v[4:7], v[160:163]
	v_mfma_f32_16x16x32_bf16 v[140:143], v[144:147], v[12:15], v[136:139]
	s_waitcnt lgkmcnt(8)
	v_mfma_f32_16x16x32_bf16 v[136:139], v[148:151], v[12:15], v[168:171]
	v_mfma_f32_16x16x32_bf16 v[164:167], v[148:151], v[4:7], v[164:167]
	s_setprio 0
	s_waitcnt lgkmcnt(7)
	s_nop 1
	v_fmamk_f32 v160, v160, 0x3e38aa3b, v203
	v_fmamk_f32 v150, v161, 0x3e38aa3b, v202
	s_waitcnt lgkmcnt(6)
	v_fmamk_f32 v159, v162, 0x3e38aa3b, v205
	v_fmamk_f32 v148, v163, 0x3e38aa3b, v204
	s_waitcnt lgkmcnt(5)
	v_fmamk_f32 v151, v164, 0x3e38aa3b, v207
	v_fmamk_f32 v146, v165, 0x3e38aa3b, v206
	s_waitcnt lgkmcnt(4)
	v_fmamk_f32 v145, v166, 0x3e38aa3b, v209
	v_fmamk_f32 v144, v167, 0x3e38aa3b, v208
	ds_read2_b64 v[202:205], v155 offset0:8 offset1:12
	ds_read2_b64 v[206:209], v156 offset0:24 offset1:28
	ds_read2_b64 v[242:245], v157 offset0:40 offset1:44
	ds_read2_b64 v[246:249], v158 offset0:56 offset1:60
	v_max3_f32 v147, v160, v150, v159
	v_max3_f32 v149, v148, v151, v146
	v_max_f32_e32 v152, v145, v144
	v_max3_f32 v147, v152, v147, v149
	v_add_f32_e32 v149, 0x41000000, v192
	v_cmp_gt_f32_e32 vcc, v147, v149
	s_cbranch_vccz .LBB0_387
	ds_bpermute_b32 v149, v233, v147
	v_max_f32_e32 v147, v147, v147
	v_mov_b32_e32 v153, v193
	s_waitcnt lgkmcnt(0)
	v_max_f32_e32 v149, v149, v149
	v_max_f32_e32 v147, v147, v149
	ds_bpermute_b32 v149, v234, v147
	s_waitcnt lgkmcnt(0)
	v_max3_f32 v152, v192, v147, v149
	v_sub_f32_e32 v147, v192, v152
	v_exp_f32_e32 v162, v147
	v_mov_b64_e32 v[192:193], v[152:153]
	v_mul_f32_e32 v196, v196, v162
	v_pk_mul_f32 v[118:119], v[118:119], v[162:163] op_sel_hi:[1,0]
	v_pk_mul_f32 v[116:117], v[116:117], v[162:163] op_sel_hi:[1,0]
	v_pk_mul_f32 v[114:115], v[114:115], v[162:163] op_sel_hi:[1,0]
	v_pk_mul_f32 v[112:113], v[112:113], v[162:163] op_sel_hi:[1,0]
	v_pk_mul_f32 v[110:111], v[110:111], v[162:163] op_sel_hi:[1,0]
	v_pk_mul_f32 v[108:109], v[108:109], v[162:163] op_sel_hi:[1,0]
	v_pk_mul_f32 v[106:107], v[106:107], v[162:163] op_sel_hi:[1,0]
	v_pk_mul_f32 v[104:105], v[104:105], v[162:163] op_sel_hi:[1,0]
	s_branch .LBB0_388

; template <int MODE>
; __device__ __forceinline__ void nsa_compute(int cur, int buf, int t, int hl, u64 mymask, const bf16x8 (&Qf)[2][2], f32x4 (&O)[4][2], float (&m)[2], float (&l)[2],
;                                             const float (&inv)[2], float* impw, char* lds) {
;     ...
;       for (int kk = 0; kk < 2; ++kk)
; #pragma unroll
;         for (int e = 0; e < 4; ++e) {
;           const int off = 32 * s2 + 16 * kk + e;
;           int idx;
;           if (MODE <= 1) { idx = base - 16 * off; idx = idx > 0 ? idx : 0; } else idx = base - off;
;           sv[kk][e] = S[kk][r][e] * (0.125f * LOG2E) + tb[r * TS + idx];
;         }
;       float pv[2][4];
;       if (MODE == 1) {
; #pragma unroll
;         for (int kk = 0; kk < 2; ++kk)
; #pragma unroll
;           for (int e = 0; e < 4; ++e) pv[kk][e] = __builtin_amdgcn_exp2f(sv[kk][e] - m[r]) * inv[r];
; #pragma unroll
;         for (int kk = 0; kk < 2; ++kk) { g1s[kk] += pv[kk][0] + pv[kk][1] + pv[kk][2] + 0.5f * pv[kk][3]; p3s[kk] += 0.5f * pv[kk][3]; }
;       } else {
;         const float mxa = fmaxf(fmaxf(sv[0][0], sv[0][1]), sv[0][2]), mxb = fmaxf(fmaxf(sv[0][3], sv[1][0]), sv[1][1]);
;         float mx = fmaxf(fmaxf(fmaxf(sv[1][2], sv[1][3]), mxa), mxb);
;         if (MODE == 2) mx = selok ? mx : -__builtin_inff();
;         if (__any(mx > m[r] + 8.0f)) {
;           mx = fmaxf(mx, __shfl_xor(mx, 16)); mx = fmaxf(mx, __shfl_xor(mx, 32));
;           const float mn = fmaxf(m[r], mx), al = __builtin_amdgcn_exp2f(m[r] - mn);
;           m[r] = mn; l[r] *= al;
;           if (MODE != 0) {
; #pragma unroll
;             for (int df = 0; df < 4; ++df) O[df][r] *= al;
;           }
;         }
;         const float me = (MODE == 2) ? (selok ? m[r] : __builtin_inff()) : m[r];
;         float ps = 0.f;
; #pragma unroll
;         for (int kk = 0; kk < 2; ++kk)
; #pragma unroll
;           for (int e = 0; e < 4; ++e) { pv[kk][e] = __builtin_amdgcn_exp2f(sv[kk][e] - me); ps += pv[kk][e]; }
;         l[r] += ps;
.LBB0_388:
	v_sub_f32_e32 v147, v160, v152
	v_exp_f32_e32 v147, v147
	v_sub_f32_e32 v149, v150, v152
	v_exp_f32_e32 v149, v149
	v_sub_f32_e32 v150, v159, v152
	v_exp_f32_e32 v150, v150
	v_sub_f32_e32 v148, v148, v152
	v_exp_f32_e32 v148, v148
	v_sub_f32_e32 v151, v151, v152
	v_add_f32_e32 v153, 0, v147
	v_exp_f32_e32 v151, v151
	v_sub_f32_e32 v146, v146, v152
	v_add_f32_e32 v153, v149, v153
	v_exp_f32_e32 v146, v146
	v_add_f32_e32 v153, v150, v153
	v_add_f32_e32 v153, v148, v153
	v_add_f32_e32 v153, v151, v153
	v_sub_f32_e32 v145, v145, v152
	v_add_f32_e32 v159, v146, v153
	v_exp_f32_e32 v153, v145
	v_sub_f32_e32 v144, v144, v152
	v_exp_f32_e32 v152, v144
	v_add_f32_e32 v145, v153, v159
	v_add_f32_e32 v144, v152, v145
	v_add_f32_e32 v196, v196, v144
	s_waitcnt lgkmcnt(7)
	v_fmamk_f32 v145, v140, 0x3e38aa3b, v211
	v_fmamk_f32 v144, v141, 0x3e38aa3b, v210
	s_waitcnt lgkmcnt(6)
	v_fmamk_f32 v141, v142, 0x3e38aa3b, v237
	v_fmamk_f32 v140, v143, 0x3e38aa3b, v236
	s_waitcnt lgkmcnt(5)
	v_fmamk_f32 v143, v136, 0x3e38aa3b, v239
	v_fmamk_f32 v142, v137, 0x3e38aa3b, v238
	s_waitcnt lgkmcnt(4)
	v_fmamk_f32 v137, v138, 0x3e38aa3b, v241
	v_fmamk_f32 v136, v139, 0x3e38aa3b, v240
	v_max3_f32 v138, v145, v144, v141
	v_max3_f32 v139, v140, v143, v142
	v_max_f32_e32 v154, v137, v136
	v_max3_f32 v138, v154, v138, v139
	v_add_f32_e32 v139, 0x41000000, v193
	v_cmp_gt_f32_e32 vcc, v138, v139
	s_cbranch_vccz .LBB0_390
	ds_bpermute_b32 v139, v233, v138
	v_max_f32_e32 v138, v138, v138
	s_waitcnt lgkmcnt(0)
	v_max_f32_e32 v139, v139, v139
	v_max_f32_e32 v138, v138, v139
	ds_bpermute_b32 v139, v234, v138
	s_waitcnt lgkmcnt(0)
	v_max3_f32 v138, v193, v138, v139
	v_sub_f32_e32 v139, v193, v138
	v_exp_f32_e32 v154, v139
	v_mov_b32_e32 v193, v138
	v_mul_f32_e32 v197, v197, v154
	v_pk_mul_f32 v[134:135], v[134:135], v[154:155] op_sel_hi:[1,0]
	v_pk_mul_f32 v[132:133], v[132:133], v[154:155] op_sel_hi:[1,0]
	v_pk_mul_f32 v[130:131], v[130:131], v[154:155] op_sel_hi:[1,0]
	v_pk_mul_f32 v[128:129], v[128:129], v[154:155] op_sel_hi:[1,0]
	v_pk_mul_f32 v[126:127], v[126:127], v[154:155] op_sel_hi:[1,0]
	v_pk_mul_f32 v[124:125], v[124:125], v[154:155] op_sel_hi:[1,0]
	v_pk_mul_f32 v[122:123], v[122:123], v[154:155] op_sel_hi:[1,0]
	v_pk_mul_f32 v[120:121], v[120:121], v[154:155] op_sel_hi:[1,0]
	s_branch .LBB0_391

; #define TIDX opaque_tid()
; __device__ __forceinline__ unsigned pk2(float lo, float hi) { const f32x2v v = {lo, hi}; const bf16x2v r = __builtin_convertvector(v, bf16x2v); return __builtin_bit_cast(unsigned, r); }
; __device__ __forceinline__ void kv_lwrite(const KVRegs& r, char* lds, int buf) {
;   const int tid = TIDX, row = tid >> 3, cq = tid & 7;
;   char* kt = lds + NSA_KT + buf * 8192 + row * 128;
;   *(u32x4*)(kt + ((cq ^ (row & 7)) << 4)) = r.k0;
;   bf16_t* vt = (bf16_t*)(lds + NSA_VT + buf * 8704) + (cq * 8) * 68 + row;
; #pragma unroll
;   for (int i = 0; i < 4; ++i) { vt[(2 * i) * 68] = (bf16_t)(r.v0[i] & 0xffffu); vt[(2 * i + 1) * 68] = (bf16_t)(r.v0[i] >> 16); }
; }
; template <int MODE>
; __device__ __forceinline__ void nsa_compute(int cur, int buf, int t, int hl, u64 mymask, const bf16x8 (&Qf)[2][2], f32x4 (&O)[4][2], float (&m)[2], float (&l)[2],
;                                             const float (&inv)[2], float* impw, char* lds) {
;     ...
;         const float me = (MODE == 2) ? (selok ? m[r] : __builtin_inff()) : m[r];
;         float ps = 0.f;
; #pragma unroll
;         for (int kk = 0; kk < 2; ++kk)
; #pragma unroll
;           for (int e = 0; e < 4; ++e) { pv[kk][e] = __builtin_amdgcn_exp2f(sv[kk][e] - me); ps += pv[kk][e]; }
;         l[r] += ps;
;       }
;       if (MODE != 0) {
;         const unsigned w0 = pk2(pv[0][0], pv[0][1]), w1 = pk2(pv[0][2], pv[0][3]), w2 = pk2(pv[1][0], pv[1][1]), w3 = pk2(pv[1][2], pv[1][3]);
;         u32x4 pw; pw.x = w0; pw.y = w1; pw.z = w2; pw.w = w3;
;         Pf[r] = __builtin_bit_cast(bf16x8, pw);
;       }
;     }
;     if (MODE != 0) {
;       bf16x8 vfr[4];
; #pragma unroll
;       for (int df = 0; df < 4; ++df) {
;         const bf16x4 va = *(const bf16x4*)(vt + (df * 16 + fr) * 68 + 32 * s2 + 4 * fq);
;         const bf16x4 vb = *(const bf16x4*)(vt + (df * 16 + fr) * 68 + 32 * s2 + 16 + 4 * fq);
;         bf16x8 vf; vf[0] = va[0]; vf[1] = va[1]; vf[2] = va[2]; vf[3] = va[3]; vf[4] = vb[0]; vf[5] = vb[1]; vf[6] = vb[2]; vf[7] = vb[3];
;         vfr[df] = vf;
;       }
;       __builtin_amdgcn_s_setprio(1);
; #pragma unroll
;       for (int df = 0; df < 4; ++df)
; #pragma unroll
;         for (int r = 0; r < 2; ++r) O[df][r] = mfma16(vfr[df], Pf[r], O[df][r]);
;       __builtin_amdgcn_s_setprio(0);
.LBB0_391:
	v_sub_f32_e32 v139, v145, v138
	v_exp_f32_e32 v168, v139
	v_sub_f32_e32 v139, v144, v138
	v_exp_f32_e32 v169, v139
	v_sub_f32_e32 v139, v141, v138
	v_exp_f32_e32 v170, v139
	v_sub_f32_e32 v139, v140, v138
	v_exp_f32_e32 v171, v139
	v_sub_f32_e32 v139, v143, v138
	v_cvt_pk_bf16_f32 v164, v147, v149
	v_cvt_pk_bf16_f32 v165, v150, v148
	v_cvt_pk_bf16_f32 v166, v151, v146
	v_cvt_pk_bf16_f32 v167, v153, v152
	v_exp_f32_e32 v172, v139
	v_sub_f32_e32 v139, v142, v138
	v_sub_f32_e32 v137, v137, v138
	v_sub_f32_e32 v136, v136, v138
	v_exp_f32_e32 v173, v139
	v_exp_f32_e32 v174, v137
	v_exp_f32_e32 v175, v136
	v_cvt_pk_bf16_f32 v198, v168, v169
	v_cvt_pk_bf16_f32 v199, v170, v171
	v_cvt_pk_bf16_f32 v200, v172, v173
	v_cvt_pk_bf16_f32 v201, v174, v175
	s_setprio 1
	s_waitcnt lgkmcnt(3)
	v_mfma_f32_16x16x32_bf16 v[136:139], v[202:205], v[164:167], v[116:119]
	v_mfma_f32_16x16x32_bf16 v[140:143], v[202:205], v[198:201], v[132:135]
	s_waitcnt lgkmcnt(2)
	v_mfma_f32_16x16x32_bf16 v[156:159], v[206:209], v[164:167], v[112:115]
	v_mfma_f32_16x16x32_bf16 v[144:147], v[206:209], v[198:201], v[128:131]
	s_waitcnt lgkmcnt(1)
	v_mfma_f32_16x16x32_bf16 v[160:163], v[242:245], v[164:167], v[108:111]
	v_mfma_f32_16x16x32_bf16 v[148:151], v[242:245], v[198:201], v[124:127]
	s_waitcnt lgkmcnt(0)
	v_mfma_f32_16x16x32_bf16 v[164:167], v[246:249], v[164:167], v[104:107]
	v_mfma_f32_16x16x32_bf16 v[152:155], v[246:249], v[198:201], v[120:123]
	s_setprio 0
	s_cmp_lt_i32 s42, 0
	s_cbranch_scc1 .LBB0_393
	v_mov_b32 v104, v179
	s_nop 0
	v_ashrrev_i32_e32 v105, 3, v104
	v_xor_b32_e32 v107, v105, v104
	v_lshlrev_b32_e32 v104, 3, v104
	v_lshlrev_b32_e32 v107, 4, v107
	v_and_b32_e32 v104, 56, v104
	v_lshlrev_b32_e32 v106, 7, v105
	v_and_b32_e32 v107, 0x70, v107
	v_mul_u32_u24_e32 v104, 0x88, v104
	v_lshlrev_b32_e32 v105, 1, v105
	v_add3_u32 v106, s64, v106, v107
	v_add3_u32 v104, s43, v104, v105
	s_waitcnt vmcnt(1)
	ds_write_b128 v106, v[64:67]
	s_waitcnt vmcnt(0)
	ds_write_b16 v104, v68 offset:16384
	ds_write_b16_d16_hi v104, v68 offset:16520
	ds_write_b16 v104, v69 offset:16656
	ds_write_b16_d16_hi v104, v69 offset:16792
	ds_write_b16 v104, v70 offset:16928
	ds_write_b16_d16_hi v104, v70 offset:17064
	ds_write_b16 v104, v71 offset:17200
	ds_write_b16_d16_hi v104, v71 offset:17336

; template <int MODE>
; __device__ __forceinline__ void nsa_compute(int cur, int buf, int t, int hl, u64 mymask, const bf16x8 (&Qf)[2][2], f32x4 (&O)[4][2], float (&m)[2], float (&l)[2],
;                                             const float (&inv)[2], float* impw, char* lds) {
;     ...
;   const bool selok = (MODE == 2) ? (((mymask >> cur) & 1ull) != 0ull) : true;
;   const float* tb = (MODE == 3) ? (const float*)(lds + NSA_TW) + hl * 640 : (const float*)(lds + NSA_T) + hl * 4160;
;   constexpr int TS = (MODE == 3) ? 640 : 4160;
;   const int base = (MODE <= 1) ? (t - 31 - 16 * (cur * 64 + 4 * fq) + 64) : (t - cur * 64 - 4 * fq + 64);
; #pragma unroll
;   for (int s2 = 0; s2 < 2; ++s2) {
;     f32x4 S[2][2] = {};
;     bf16x8 kfr[2][2];
; #pragma unroll
;     for (int ks = 0; ks < 2; ++ks)
; #pragma unroll
;       for (int kk = 0; kk < 2; ++kk) kfr[ks][kk] = *(const bf16x8*)(kt + (32 * s2 + 16 * kk + fr) * 128 + (((ks * 4 + fq) ^ (fr & 7)) << 4));
;     __builtin_amdgcn_s_setprio(1);
; #pragma unroll
;     for (int ks = 0; ks < 2; ++ks)
; #pragma unroll
;       for (int kk = 0; kk < 2; ++kk)
; #pragma unroll
;         for (int r = 0; r < 2; ++r) S[kk][r] = mfma16(kfr[ks][kk], Qf[r][ks], S[kk][r]);
;     __builtin_amdgcn_s_setprio(0);
;     bf16x8 Pf[2];
;     float g1s[2] = {0.f, 0.f}, p3s[2] = {0.f, 0.f};
; #pragma unroll
;     for (int r = 0; r < 2; ++r) {
;       float sv[2][4];
; #pragma unroll
;       for (int kk = 0; kk < 2; ++kk)
; #pragma unroll
;         for (int e = 0; e < 4; ++e) {
;           const int off = 32 * s2 + 16 * kk + e;
;           int idx;
;           if (MODE <= 1) { idx = base - 16 * off; idx = idx > 0 ? idx : 0; } else idx = base - off;
;           sv[kk][e] = S[kk][r][e] * (0.125f * LOG2E) + tb[r * TS + idx];
;         }
;       float pv[2][4];
;       if (MODE == 1) {
; #pragma unroll
;         for (int kk = 0; kk < 2; ++kk)
; #pragma unroll
;           for (int e = 0; e < 4; ++e) pv[kk][e] = __builtin_amdgcn_exp2f(sv[kk][e] - m[r]) * inv[r];
; #pragma unroll
;         for (int kk = 0; kk < 2; ++kk) { g1s[kk] += pv[kk][0] + pv[kk][1] + pv[kk][2] + 0.5f * pv[kk][3]; p3s[kk] += 0.5f * pv[kk][3]; }
;       } else {
;         const float mxa = fmaxf(fmaxf(sv[0][0], sv[0][1]), sv[0][2]), mxb = fmaxf(fmaxf(sv[0][3], sv[1][0]), sv[1][1]);
;         float mx = fmaxf(fmaxf(fmaxf(sv[1][2], sv[1][3]), mxa), mxb);
.LBB0_436:
	s_mov_b32 s17, s75
	s_lshl_b64 s[30:31], 1, s17
	v_mov_b32 v74, v179
	v_and_b32_e32 v73, s31, v187
	v_lshrrev_b32_e32 v75, 4, v74
	v_bfe_u32 v80, v74, 4, 2
	v_and_b32_e32 v72, s30, v186
	v_and_b32_e32 v81, 7, v74
	v_and_b32_e32 v94, 15, v74
	s_lshl_b32 s63, s74, 13
	v_cmp_eq_u64_e64 s[36:37], 0, v[72:73]
	v_lshlrev_b32_e32 v95, 2, v80
	v_bitop3_b32 v72, v75, v81, 3 bitop3:0x6c
	v_bitop3_b32 v80, v80, v81, 4 bitop3:0x36
	v_lshlrev_b32_e32 v91, 7, v94
	v_lshl_or_b32 v92, v72, 4, s63
	v_lshl_or_b32 v93, v80, 4, s63
	v_or_b32_e32 v76, v92, v91
	v_or_b32_e32 v84, v93, v91
	ds_read_b128 v[72:75], v76
	ds_read_b128 v[76:79], v76 offset:2048
	ds_read_b128 v[80:83], v84
	ds_read_b128 v[84:87], v84 offset:2048
	s_mov_b32 s75, s46
	v_sub_u32_e32 v251, v180, v95
	v_lshl_add_u32 v251, v251, 2, v181
	s_lshl_b32 s17, s17, 8
	v_subrev_u32_e32 v250, s17, v251
	v_add_u32_e32 v249, 0x8400, v250
	v_add_u32_e32 v248, 0xc500, v250
	ds_read2_b32 v[114:115], v249 offset0:63 offset1:64
	ds_read2_b32 v[116:117], v249 offset0:61 offset1:62
	ds_read2_b32 v[118:119], v249 offset0:47 offset1:48
	ds_read2_b32 v[138:139], v249 offset0:45 offset1:46
	ds_read2_b32 v[140:141], v248 offset0:63 offset1:64
	ds_read2_b32 v[142:143], v248 offset0:61 offset1:62
	ds_read2_b32 v[144:145], v248 offset0:47 offset1:48
	ds_read2_b32 v[148:149], v248 offset0:45 offset1:46
	s_setprio 1
	s_waitcnt lgkmcnt(11)
	v_mfma_f32_16x16x32_bf16 v[96:99], v[72:75], v[0:3], 0
	v_mfma_f32_16x16x32_bf16 v[72:75], v[72:75], v[8:11], 0
	s_waitcnt lgkmcnt(10)
	v_mfma_f32_16x16x32_bf16 v[104:107], v[76:79], v[8:11], 0
	v_mfma_f32_16x16x32_bf16 v[100:103], v[76:79], v[0:3], 0
	s_waitcnt lgkmcnt(9)
	v_mfma_f32_16x16x32_bf16 v[96:99], v[80:83], v[4:7], v[96:99]
	v_mfma_f32_16x16x32_bf16 v[76:79], v[80:83], v[12:15], v[72:75]
	s_waitcnt lgkmcnt(8)
	v_mfma_f32_16x16x32_bf16 v[72:75], v[84:87], v[12:15], v[104:107]
	v_mfma_f32_16x16x32_bf16 v[100:103], v[84:87], v[4:7], v[100:103]
	s_setprio 0
	v_sub_u32_e32 v80, v180, v95
	v_lshl_add_u32 v80, v80, 2, v181
	v_subrev_u32_e32 v90, s17, v80
	s_waitcnt lgkmcnt(7)
	v_fmamk_f32 v87, v96, 0x3e38aa3b, v115
	v_fmamk_f32 v86, v97, 0x3e38aa3b, v114
	s_waitcnt lgkmcnt(6)
	v_fmamk_f32 v83, v98, 0x3e38aa3b, v117
	v_fmamk_f32 v82, v99, 0x3e38aa3b, v116
	s_waitcnt lgkmcnt(5)
	v_fmamk_f32 v81, v100, 0x3e38aa3b, v119
	v_fmamk_f32 v80, v101, 0x3e38aa3b, v118
	s_waitcnt lgkmcnt(4)
	v_fmamk_f32 v97, v102, 0x3e38aa3b, v139
	v_fmamk_f32 v84, v103, 0x3e38aa3b, v138
	s_lshl_b32 s17, s74, 9
	v_mul_u32_u24_e32 v114, 0x44, v94
	s_add_i32 s71, s63, s17
	v_lshlrev_b32_e32 v115, 1, v114
	v_lshlrev_b32_e32 v116, 1, v95
	v_add3_u32 v117, s71, v115, v116
	v_add_u32_e32 v118, 0x4000, v117
	ds_read2_b64 v[150:153], v118 offset1:4
	v_add_u32_e32 v119, 0x4800, v117
	v_add_u32_e32 v138, 0x5000, v117
	v_add_u32_e32 v139, 0x5800, v117
	ds_read2_b64 v[154:157], v119 offset0:16 offset1:20
	ds_read2_b64 v[168:171], v138 offset0:32 offset1:36
	ds_read2_b64 v[172:175], v139 offset0:48 offset1:52
	v_max3_f32 v85, v87, v86, v83
	v_max3_f32 v88, v82, v81, v80
	v_max_f32_e32 v89, v97, v84
	v_max3_f32 v85, v89, v85, v88
	v_cndmask_b32_e64 v85, v85, v225, s[36:37]
	v_add_f32_e32 v88, 0x41000000, v188
	v_cmp_gt_f32_e32 vcc, v85, v88
	s_cbranch_vccz .LBB0_438
	ds_bpermute_b32 v88, v233, v85
	v_max_f32_e32 v85, v85, v85
	v_mov_b32_e32 v89, v189
	s_waitcnt lgkmcnt(0)
	v_max_f32_e32 v88, v88, v88
	v_max_f32_e32 v85, v85, v88
	ds_bpermute_b32 v88, v234, v85
	s_waitcnt lgkmcnt(0)
	v_max3_f32 v88, v188, v85, v88
	v_sub_f32_e32 v85, v188, v88
	v_exp_f32_e32 v96, v85
	v_mov_b64_e32 v[188:189], v[88:89]
	v_mul_f32_e32 v190, v190, v96
	v_pk_mul_f32 v[18:19], v[18:19], v[96:97] op_sel_hi:[1,0]
	v_pk_mul_f32 v[16:17], v[16:17], v[96:97] op_sel_hi:[1,0]
	v_pk_mul_f32 v[26:27], v[26:27], v[96:97] op_sel_hi:[1,0]
	v_pk_mul_f32 v[24:25], v[24:25], v[96:97] op_sel_hi:[1,0]
	v_pk_mul_f32 v[34:35], v[34:35], v[96:97] op_sel_hi:[1,0]
	v_pk_mul_f32 v[32:33], v[32:33], v[96:97] op_sel_hi:[1,0]
	v_pk_mul_f32 v[42:43], v[42:43], v[96:97] op_sel_hi:[1,0]
	v_pk_mul_f32 v[40:41], v[40:41], v[96:97] op_sel_hi:[1,0]
	s_branch .LBB0_439

; template <int MODE>
; __device__ __forceinline__ void nsa_compute(int cur, int buf, int t, int hl, u64 mymask, const bf16x8 (&Qf)[2][2], f32x4 (&O)[4][2], float (&m)[2], float (&l)[2],
;                                             const float (&inv)[2], float* impw, char* lds) {
;     ...
;       for (int kk = 0; kk < 2; ++kk)
; #pragma unroll
;         for (int e = 0; e < 4; ++e) {
;           const int off = 32 * s2 + 16 * kk + e;
;           int idx;
;           if (MODE <= 1) { idx = base - 16 * off; idx = idx > 0 ? idx : 0; } else idx = base - off;
;           sv[kk][e] = S[kk][r][e] * (0.125f * LOG2E) + tb[r * TS + idx];
;         }
;       float pv[2][4];
;       if (MODE == 1) {
; #pragma unroll
;         for (int kk = 0; kk < 2; ++kk)
; #pragma unroll
;           for (int e = 0; e < 4; ++e) pv[kk][e] = __builtin_amdgcn_exp2f(sv[kk][e] - m[r]) * inv[r];
; #pragma unroll
;         for (int kk = 0; kk < 2; ++kk) { g1s[kk] += pv[kk][0] + pv[kk][1] + pv[kk][2] + 0.5f * pv[kk][3]; p3s[kk] += 0.5f * pv[kk][3]; }
;       } else {
;         const float mxa = fmaxf(fmaxf(sv[0][0], sv[0][1]), sv[0][2]), mxb = fmaxf(fmaxf(sv[0][3], sv[1][0]), sv[1][1]);
;         float mx = fmaxf(fmaxf(fmaxf(sv[1][2], sv[1][3]), mxa), mxb);
;         if (MODE == 2) mx = selok ? mx : -__builtin_inff();
;         if (__any(mx > m[r] + 8.0f)) {
;           mx = fmaxf(mx, __shfl_xor(mx, 16)); mx = fmaxf(mx, __shfl_xor(mx, 32));
;           const float mn = fmaxf(m[r], mx), al = __builtin_amdgcn_exp2f(m[r] - mn);
;           m[r] = mn; l[r] *= al;
;           if (MODE != 0) {
; #pragma unroll
;             for (int df = 0; df < 4; ++df) O[df][r] *= al;
;           }
;         }
;         const float me = (MODE == 2) ? (selok ? m[r] : __builtin_inff()) : m[r];
;         float ps = 0.f;
; #pragma unroll
;         for (int kk = 0; kk < 2; ++kk)
; #pragma unroll
;           for (int e = 0; e < 4; ++e) { pv[kk][e] = __builtin_amdgcn_exp2f(sv[kk][e] - me); ps += pv[kk][e]; }
;         l[r] += ps;
.LBB0_439:
	v_cndmask_b32_e64 v98, v88, v228, s[36:37]
	v_sub_f32_e32 v85, v87, v98
	v_exp_f32_e32 v85, v85
	v_sub_f32_e32 v86, v86, v98
	v_exp_f32_e32 v86, v86
	v_sub_f32_e32 v83, v83, v98
	v_add_f32_e32 v87, 0, v85
	v_sub_f32_e32 v82, v82, v98
	v_add_f32_e32 v88, v86, v87
	v_exp_f32_e32 v87, v83
	v_sub_f32_e32 v81, v81, v98
	v_exp_f32_e32 v89, v81
	v_sub_f32_e32 v80, v80, v98
	v_add_f32_e32 v83, v87, v88
	v_exp_f32_e32 v88, v82
	v_exp_f32_e32 v96, v80
	v_add_f32_e32 v82, v88, v83
	v_add_f32_e32 v81, v89, v82
	v_add_f32_e32 v80, v96, v81
	v_sub_f32_e32 v81, v97, v98
	v_exp_f32_e32 v97, v81
	v_sub_f32_e32 v81, v84, v98
	v_exp_f32_e32 v84, v81
	v_add_f32_e32 v80, v97, v80
	v_add_f32_e32 v80, v84, v80
	v_add_f32_e32 v190, v190, v80
	s_waitcnt lgkmcnt(7)
	v_fmamk_f32 v81, v76, 0x3e38aa3b, v141
	v_fmamk_f32 v80, v77, 0x3e38aa3b, v140
	s_waitcnt lgkmcnt(6)
	v_fmamk_f32 v78, v78, 0x3e38aa3b, v143
	v_fmamk_f32 v82, v79, 0x3e38aa3b, v142
	s_waitcnt lgkmcnt(5)
	v_fmamk_f32 v77, v72, 0x3e38aa3b, v145
	v_fmamk_f32 v76, v73, 0x3e38aa3b, v144
	s_waitcnt lgkmcnt(4)
	v_fmamk_f32 v73, v74, 0x3e38aa3b, v149
	v_fmamk_f32 v72, v75, 0x3e38aa3b, v148
	v_max3_f32 v74, v81, v80, v78
	v_max3_f32 v75, v82, v77, v76
	v_max_f32_e32 v79, v73, v72
	v_max3_f32 v74, v79, v74, v75
	v_cndmask_b32_e64 v74, v74, v225, s[36:37]
	v_add_f32_e32 v75, 0x41000000, v189
	v_cmp_gt_f32_e32 vcc, v74, v75
	s_cbranch_vccz .LBB0_441
	ds_bpermute_b32 v75, v233, v74
	v_max_f32_e32 v74, v74, v74
	s_waitcnt lgkmcnt(0)
	v_max_f32_e32 v75, v75, v75
	v_max_f32_e32 v74, v74, v75
	ds_bpermute_b32 v75, v234, v74
	s_waitcnt lgkmcnt(0)
	v_max3_f32 v74, v189, v74, v75
	v_sub_f32_e32 v75, v189, v74
	v_exp_f32_e32 v98, v75
	v_mov_b32_e32 v189, v74
	v_mul_f32_e32 v191, v191, v98
	v_pk_mul_f32 v[22:23], v[22:23], v[98:99] op_sel_hi:[1,0]
	v_pk_mul_f32 v[20:21], v[20:21], v[98:99] op_sel_hi:[1,0]
	v_pk_mul_f32 v[30:31], v[30:31], v[98:99] op_sel_hi:[1,0]
	v_pk_mul_f32 v[28:29], v[28:29], v[98:99] op_sel_hi:[1,0]
	v_pk_mul_f32 v[38:39], v[38:39], v[98:99] op_sel_hi:[1,0]
	v_pk_mul_f32 v[36:37], v[36:37], v[98:99] op_sel_hi:[1,0]
	v_pk_mul_f32 v[46:47], v[46:47], v[98:99] op_sel_hi:[1,0]
	v_pk_mul_f32 v[44:45], v[44:45], v[98:99] op_sel_hi:[1,0]
	s_branch .LBB0_442

; template <int MODE>
; __device__ __forceinline__ void nsa_compute(int cur, int buf, int t, int hl, u64 mymask, const bf16x8 (&Qf)[2][2], f32x4 (&O)[4][2], float (&m)[2], float (&l)[2],
;                                             const float (&inv)[2], float* impw, char* lds) {
;     ...
; #pragma unroll
;     for (int ks = 0; ks < 2; ++ks)
; #pragma unroll
;       for (int kk = 0; kk < 2; ++kk) kfr[ks][kk] = *(const bf16x8*)(kt + (32 * s2 + 16 * kk + fr) * 128 + (((ks * 4 + fq) ^ (fr & 7)) << 4));
;     __builtin_amdgcn_s_setprio(1);
; #pragma unroll
;     for (int ks = 0; ks < 2; ++ks)
; #pragma unroll
;       for (int kk = 0; kk < 2; ++kk)
; #pragma unroll
;         for (int r = 0; r < 2; ++r) S[kk][r] = mfma16(kfr[ks][kk], Qf[r][ks], S[kk][r]);
;     __builtin_amdgcn_s_setprio(0);
;     bf16x8 Pf[2];
;     float g1s[2] = {0.f, 0.f}, p3s[2] = {0.f, 0.f};
; #pragma unroll
;     for (int r = 0; r < 2; ++r) {
;       float sv[2][4];
; #pragma unroll
;       for (int kk = 0; kk < 2; ++kk)
; #pragma unroll
;         for (int e = 0; e < 4; ++e) {
;     ...
;         const float me = (MODE == 2) ? (selok ? m[r] : __builtin_inff()) : m[r];
;         float ps = 0.f;
; #pragma unroll
;         for (int kk = 0; kk < 2; ++kk)
; #pragma unroll
;           for (int e = 0; e < 4; ++e) { pv[kk][e] = __builtin_amdgcn_exp2f(sv[kk][e] - me); ps += pv[kk][e]; }
;         l[r] += ps;
;       }
;       if (MODE != 0) {
;         const unsigned w0 = pk2(pv[0][0], pv[0][1]), w1 = pk2(pv[0][2], pv[0][3]), w2 = pk2(pv[1][0], pv[1][1]), w3 = pk2(pv[1][2], pv[1][3]);
;         u32x4 pw; pw.x = w0; pw.y = w1; pw.z = w2; pw.w = w3;
;         Pf[r] = __builtin_bit_cast(bf16x8, pw);
;       }
;     }
;     if (MODE != 0) {
;       bf16x8 vfr[4];
; #pragma unroll
;       for (int df = 0; df < 4; ++df) {
;         const bf16x4 va = *(const bf16x4*)(vt + (df * 16 + fr) * 68 + 32 * s2 + 4 * fq);
;         const bf16x4 vb = *(const bf16x4*)(vt + (df * 16 + fr) * 68 + 32 * s2 + 16 + 4 * fq);
;         bf16x8 vf; vf[0] = va[0]; vf[1] = va[1]; vf[2] = va[2]; vf[3] = va[3]; vf[4] = vb[0]; vf[5] = vb[1]; vf[6] = vb[2]; vf[7] = vb[3];
;         vfr[df] = vf;
;       }
;       __builtin_amdgcn_s_setprio(1);
; #pragma unroll
;       for (int df = 0; df < 4; ++df)
; #pragma unroll
;         for (int r = 0; r < 2; ++r) O[df][r] = mfma16(vfr[df], Pf[r], O[df][r]);
;       __builtin_amdgcn_s_setprio(0);
;     }
.LBB0_442:
	v_cndmask_b32_e64 v74, v74, v228, s[36:37]
	v_sub_f32_e32 v75, v81, v74
	v_exp_f32_e32 v75, v75
	v_sub_f32_e32 v80, v80, v74
	v_exp_f32_e32 v80, v80
	v_sub_f32_e32 v78, v78, v74
	v_exp_f32_e32 v78, v78
	v_sub_f32_e32 v81, v82, v74
	v_exp_f32_e32 v81, v81
	v_sub_f32_e32 v77, v77, v74
	v_add_f32_e32 v79, 0, v75
	v_exp_f32_e32 v77, v77
	v_sub_f32_e32 v76, v76, v74
	v_add_f32_e32 v79, v80, v79
	v_exp_f32_e32 v76, v76
	v_sub_f32_e32 v73, v73, v74
	v_add_f32_e32 v79, v78, v79
	v_exp_f32_e32 v73, v73
	v_sub_f32_e32 v72, v72, v74
	v_add_f32_e32 v79, v81, v79
	v_exp_f32_e32 v72, v72
	v_add_f32_e32 v79, v77, v79
	v_add_f32_e32 v79, v76, v79
	v_add_f32_e32 v79, v73, v79
	s_lshl_b32 s17, s74, 9
	v_add_f32_e32 v74, v72, v79
	v_cvt_pk_bf16_f32 v101, v73, v72
	v_mul_u32_u24_e32 v72, 0x44, v94
	s_add_i32 s71, s63, s17
	v_lshlrev_b32_e32 v72, 1, v72
	v_lshlrev_b32_e32 v73, 1, v95
	v_add3_u32 v72, s71, v72, v73
	v_add_u32_e32 v94, 0x4000, v72
	v_cvt_pk_bf16_f32 v87, v87, v88
	v_cvt_pk_bf16_f32 v88, v89, v96
	v_cvt_pk_bf16_f32 v89, v97, v84
	v_cvt_pk_bf16_f32 v99, v78, v81
	v_cvt_pk_bf16_f32 v100, v77, v76
	v_add_u32_e32 v95, 0x4800, v72
	v_add_u32_e32 v96, 0x5000, v72
	v_add_u32_e32 v97, 0x5800, v72
	v_cvt_pk_bf16_f32 v86, v85, v86
	v_add_f32_e32 v191, v191, v74
	v_cvt_pk_bf16_f32 v98, v75, v80
	s_setprio 1
	s_waitcnt lgkmcnt(3)
	v_mfma_f32_16x16x32_bf16 v[72:75], v[150:153], v[86:89], v[16:19]
	v_mfma_f32_16x16x32_bf16 v[80:83], v[150:153], v[98:101], v[20:23]
	s_waitcnt lgkmcnt(2)
	v_mfma_f32_16x16x32_bf16 v[24:27], v[154:157], v[86:89], v[24:27]
	v_mfma_f32_16x16x32_bf16 v[76:79], v[154:157], v[98:101], v[28:31]
	s_waitcnt lgkmcnt(1)
	v_mfma_f32_16x16x32_bf16 v[20:23], v[168:171], v[86:89], v[32:35]
	v_mfma_f32_16x16x32_bf16 v[32:35], v[168:171], v[98:101], v[36:39]
	s_waitcnt lgkmcnt(0)
	v_mfma_f32_16x16x32_bf16 v[16:19], v[172:175], v[86:89], v[40:43]
	v_mfma_f32_16x16x32_bf16 v[28:31], v[172:175], v[98:101], v[44:47]
	s_setprio 0
	s_nop 0
	v_add_u32_e32 v40, v92, v91
	v_add_u32_e32 v84, v93, v91
	ds_read_b128 v[36:39], v40 offset:4096
	ds_read_b128 v[40:43], v40 offset:6144
	ds_read_b128 v[44:47], v84 offset:4096
	ds_read_b128 v[84:87], v84 offset:6144
	v_add_u32_e32 v251, 0x8400, v90
	v_add_u32_e32 v250, 0xc500, v90
	ds_read2_b32 v[138:139], v251 offset0:31 offset1:32
	ds_read2_b32 v[140:141], v251 offset0:29 offset1:30
	ds_read2_b32 v[142:143], v251 offset0:15 offset1:16
	ds_read2_b32 v[148:149], v251 offset0:13 offset1:14
	ds_read2_b32 v[150:151], v250 offset0:31 offset1:32
	ds_read2_b32 v[152:153], v250 offset0:29 offset1:30
	ds_read2_b32 v[154:155], v250 offset0:15 offset1:16
	ds_read2_b32 v[156:157], v250 offset0:13 offset1:14
	s_setprio 1
	s_waitcnt lgkmcnt(11)
	v_mfma_f32_16x16x32_bf16 v[98:101], v[36:39], v[0:3], 0
	v_mfma_f32_16x16x32_bf16 v[36:39], v[36:39], v[8:11], 0
	s_waitcnt lgkmcnt(10)
	v_mfma_f32_16x16x32_bf16 v[106:109], v[40:43], v[8:11], 0
	v_mfma_f32_16x16x32_bf16 v[102:105], v[40:43], v[0:3], 0
	s_waitcnt lgkmcnt(9)
	v_mfma_f32_16x16x32_bf16 v[40:43], v[44:47], v[12:15], v[36:39]
	s_waitcnt lgkmcnt(8)
	v_mfma_f32_16x16x32_bf16 v[36:39], v[84:87], v[12:15], v[106:109]
	v_mfma_f32_16x16x32_bf16 v[98:101], v[44:47], v[4:7], v[98:101]
	v_mfma_f32_16x16x32_bf16 v[102:105], v[84:87], v[4:7], v[102:105]
	s_setprio 0
	s_waitcnt lgkmcnt(7)
	s_nop 4
	v_fmamk_f32 v91, v98, 0x3e38aa3b, v139
	v_fmamk_f32 v84, v99, 0x3e38aa3b, v138
	s_waitcnt lgkmcnt(6)
	v_fmamk_f32 v85, v100, 0x3e38aa3b, v141
	v_fmamk_f32 v46, v101, 0x3e38aa3b, v140
	s_waitcnt lgkmcnt(5)
	v_fmamk_f32 v45, v102, 0x3e38aa3b, v143
	v_fmamk_f32 v44, v103, 0x3e38aa3b, v142
	v_max3_f32 v47, v91, v84, v85
	s_waitcnt lgkmcnt(4)
	v_fmamk_f32 v92, v104, 0x3e38aa3b, v149
	v_fmamk_f32 v86, v105, 0x3e38aa3b, v148
	ds_read2_b64 v[138:141], v94 offset0:8 offset1:12
	ds_read2_b64 v[168:171], v95 offset0:24 offset1:28
	ds_read2_b64 v[108:111], v96 offset0:40 offset1:44
	ds_read2_b64 v[112:115], v97 offset0:56 offset1:60
	v_max3_f32 v87, v46, v45, v44
	v_max_f32_e32 v88, v92, v86
	v_max3_f32 v47, v88, v47, v87
	v_cndmask_b32_e64 v47, v47, v225, s[36:37]
	v_add_f32_e32 v87, 0x41000000, v188
	v_cmp_gt_f32_e32 vcc, v47, v87
	s_cbranch_vccz .LBB0_444
	ds_bpermute_b32 v87, v233, v47
	v_max_f32_e32 v47, v47, v47
	v_mov_b32_e32 v89, v189
	s_waitcnt lgkmcnt(0)
	v_max_f32_e32 v87, v87, v87
	v_max_f32_e32 v47, v47, v87
	ds_bpermute_b32 v87, v234, v47
	s_waitcnt lgkmcnt(0)
	v_max3_f32 v88, v188, v47, v87
	v_sub_f32_e32 v47, v188, v88
	v_exp_f32_e32 v98, v47
	v_mov_b64_e32 v[188:189], v[88:89]
	v_mul_f32_e32 v190, v190, v98
	v_pk_mul_f32 v[74:75], v[74:75], v[98:99] op_sel_hi:[1,0]
	v_pk_mul_f32 v[72:73], v[72:73], v[98:99] op_sel_hi:[1,0]
	v_pk_mul_f32 v[26:27], v[26:27], v[98:99] op_sel_hi:[1,0]
	v_pk_mul_f32 v[24:25], v[24:25], v[98:99] op_sel_hi:[1,0]
	v_pk_mul_f32 v[22:23], v[22:23], v[98:99] op_sel_hi:[1,0]
	v_pk_mul_f32 v[20:21], v[20:21], v[98:99] op_sel_hi:[1,0]
	v_pk_mul_f32 v[18:19], v[18:19], v[98:99] op_sel_hi:[1,0]
	v_pk_mul_f32 v[16:17], v[16:17], v[98:99] op_sel_hi:[1,0]
	s_branch .LBB0_445

; template <int MODE>
; __device__ __forceinline__ void nsa_compute(int cur, int buf, int t, int hl, u64 mymask, const bf16x8 (&Qf)[2][2], f32x4 (&O)[4][2], float (&m)[2], float (&l)[2],
;                                             const float (&inv)[2], float* impw, char* lds) {
;     ...
;       for (int kk = 0; kk < 2; ++kk)
; #pragma unroll
;         for (int e = 0; e < 4; ++e) {
;           const int off = 32 * s2 + 16 * kk + e;
;           int idx;
;           if (MODE <= 1) { idx = base - 16 * off; idx = idx > 0 ? idx : 0; } else idx = base - off;
;           sv[kk][e] = S[kk][r][e] * (0.125f * LOG2E) + tb[r * TS + idx];
;         }
;       float pv[2][4];
;       if (MODE == 1) {
; #pragma unroll
;         for (int kk = 0; kk < 2; ++kk)
; #pragma unroll
;           for (int e = 0; e < 4; ++e) pv[kk][e] = __builtin_amdgcn_exp2f(sv[kk][e] - m[r]) * inv[r];
; #pragma unroll
;         for (int kk = 0; kk < 2; ++kk) { g1s[kk] += pv[kk][0] + pv[kk][1] + pv[kk][2] + 0.5f * pv[kk][3]; p3s[kk] += 0.5f * pv[kk][3]; }
;       } else {
;         const float mxa = fmaxf(fmaxf(sv[0][0], sv[0][1]), sv[0][2]), mxb = fmaxf(fmaxf(sv[0][3], sv[1][0]), sv[1][1]);
;         float mx = fmaxf(fmaxf(fmaxf(sv[1][2], sv[1][3]), mxa), mxb);
;         if (MODE == 2) mx = selok ? mx : -__builtin_inff();
;         if (__any(mx > m[r] + 8.0f)) {
;           mx = fmaxf(mx, __shfl_xor(mx, 16)); mx = fmaxf(mx, __shfl_xor(mx, 32));
;           const float mn = fmaxf(m[r], mx), al = __builtin_amdgcn_exp2f(m[r] - mn);
;           m[r] = mn; l[r] *= al;
;           if (MODE != 0) {
; #pragma unroll
;             for (int df = 0; df < 4; ++df) O[df][r] *= al;
;           }
;         }
;         const float me = (MODE == 2) ? (selok ? m[r] : __builtin_inff()) : m[r];
;         float ps = 0.f;
; #pragma unroll
;         for (int kk = 0; kk < 2; ++kk)
; #pragma unroll
;           for (int e = 0; e < 4; ++e) { pv[kk][e] = __builtin_amdgcn_exp2f(sv[kk][e] - me); ps += pv[kk][e]; }
;         l[r] += ps;
.LBB0_445:
	v_cndmask_b32_e64 v93, v88, v228, s[36:37]
	v_sub_f32_e32 v47, v91, v93
	v_exp_f32_e32 v47, v47
	v_sub_f32_e32 v84, v84, v93
	v_exp_f32_e32 v84, v84
	v_sub_f32_e32 v85, v85, v93
	v_exp_f32_e32 v85, v85
	v_sub_f32_e32 v46, v46, v93
	v_exp_f32_e32 v46, v46
	v_add_f32_e32 v87, 0, v47
	v_add_f32_e32 v87, v84, v87
	v_add_f32_e32 v87, v85, v87
	v_sub_f32_e32 v45, v45, v93
	v_add_f32_e32 v88, v46, v87
	v_exp_f32_e32 v87, v45
	v_sub_f32_e32 v44, v44, v93
	v_add_f32_e32 v45, v87, v88
	v_exp_f32_e32 v88, v44
	s_nop 0
	v_add_f32_e32 v44, v88, v45
	v_sub_f32_e32 v45, v92, v93
	v_exp_f32_e32 v89, v45
	v_sub_f32_e32 v45, v86, v93
	v_exp_f32_e32 v86, v45
	v_add_f32_e32 v44, v89, v44
	v_add_f32_e32 v44, v86, v44
	v_add_f32_e32 v190, v190, v44
	s_waitcnt lgkmcnt(7)
	v_fmamk_f32 v45, v40, 0x3e38aa3b, v151
	v_fmamk_f32 v44, v41, 0x3e38aa3b, v150
	s_waitcnt lgkmcnt(6)
	v_fmamk_f32 v41, v42, 0x3e38aa3b, v153
	v_fmamk_f32 v40, v43, 0x3e38aa3b, v152
	s_waitcnt lgkmcnt(5)
	v_fmamk_f32 v43, v36, 0x3e38aa3b, v155
	v_fmamk_f32 v42, v37, 0x3e38aa3b, v154
	s_waitcnt lgkmcnt(4)
	v_fmamk_f32 v90, v38, 0x3e38aa3b, v157
	v_fmamk_f32 v36, v39, 0x3e38aa3b, v156
	v_max3_f32 v37, v45, v44, v41
	v_max3_f32 v38, v40, v43, v42
	v_max_f32_e32 v39, v90, v36
	v_max3_f32 v37, v39, v37, v38
	v_cndmask_b32_e64 v37, v37, v225, s[36:37]
	v_add_f32_e32 v38, 0x41000000, v189
	v_cmp_gt_f32_e32 vcc, v37, v38
	s_cbranch_vccz .LBB0_447
	ds_bpermute_b32 v38, v233, v37
	v_max_f32_e32 v37, v37, v37
	s_waitcnt lgkmcnt(0)
	v_max_f32_e32 v38, v38, v38
	v_max_f32_e32 v37, v37, v38
	ds_bpermute_b32 v38, v234, v37
	s_waitcnt lgkmcnt(0)
	v_max3_f32 v37, v189, v37, v38
	v_sub_f32_e32 v38, v189, v37
	v_exp_f32_e32 v38, v38
	v_mov_b32_e32 v189, v37
	v_mul_f32_e32 v191, v191, v38
	v_pk_mul_f32 v[82:83], v[82:83], v[38:39] op_sel_hi:[1,0]
	v_pk_mul_f32 v[80:81], v[80:81], v[38:39] op_sel_hi:[1,0]
	v_pk_mul_f32 v[78:79], v[78:79], v[38:39] op_sel_hi:[1,0]
	v_pk_mul_f32 v[76:77], v[76:77], v[38:39] op_sel_hi:[1,0]
	v_pk_mul_f32 v[34:35], v[34:35], v[38:39] op_sel_hi:[1,0]
	v_pk_mul_f32 v[32:33], v[32:33], v[38:39] op_sel_hi:[1,0]
	v_pk_mul_f32 v[30:31], v[30:31], v[38:39] op_sel_hi:[1,0]
	v_pk_mul_f32 v[28:29], v[28:29], v[38:39] op_sel_hi:[1,0]
	v_mov_b64_e32 v[144:145], v[190:191]
	s_branch .LBB0_448

; #define TIDX opaque_tid()
; __device__ __forceinline__ unsigned pk2(float lo, float hi) { const f32x2v v = {lo, hi}; const bf16x2v r = __builtin_convertvector(v, bf16x2v); return __builtin_bit_cast(unsigned, r); }
; __device__ __forceinline__ void kv_lwrite(const KVRegs& r, char* lds, int buf) {
;   const int tid = TIDX, row = tid >> 3, cq = tid & 7;
;   char* kt = lds + NSA_KT + buf * 8192 + row * 128;
;   *(u32x4*)(kt + ((cq ^ (row & 7)) << 4)) = r.k0;
;   bf16_t* vt = (bf16_t*)(lds + NSA_VT + buf * 8704) + (cq * 8) * 68 + row;
; #pragma unroll
;   for (int i = 0; i < 4; ++i) { vt[(2 * i) * 68] = (bf16_t)(r.v0[i] & 0xffffu); vt[(2 * i + 1) * 68] = (bf16_t)(r.v0[i] >> 16); }
; }
; template <int MODE>
; __device__ __forceinline__ void nsa_compute(int cur, int buf, int t, int hl, u64 mymask, const bf16x8 (&Qf)[2][2], f32x4 (&O)[4][2], float (&m)[2], float (&l)[2],
;                                             const float (&inv)[2], float* impw, char* lds) {
;     ...
;         const float me = (MODE == 2) ? (selok ? m[r] : __builtin_inff()) : m[r];
;         float ps = 0.f;
; #pragma unroll
;         for (int kk = 0; kk < 2; ++kk)
; #pragma unroll
;           for (int e = 0; e < 4; ++e) { pv[kk][e] = __builtin_amdgcn_exp2f(sv[kk][e] - me); ps += pv[kk][e]; }
;         l[r] += ps;
;       }
;       if (MODE != 0) {
;         const unsigned w0 = pk2(pv[0][0], pv[0][1]), w1 = pk2(pv[0][2], pv[0][3]), w2 = pk2(pv[1][0], pv[1][1]), w3 = pk2(pv[1][2], pv[1][3]);
;         u32x4 pw; pw.x = w0; pw.y = w1; pw.z = w2; pw.w = w3;
;         Pf[r] = __builtin_bit_cast(bf16x8, pw);
;       }
;     }
;     if (MODE != 0) {
;       bf16x8 vfr[4];
; #pragma unroll
;       for (int df = 0; df < 4; ++df) {
;         const bf16x4 va = *(const bf16x4*)(vt + (df * 16 + fr) * 68 + 32 * s2 + 4 * fq);
;         const bf16x4 vb = *(const bf16x4*)(vt + (df * 16 + fr) * 68 + 32 * s2 + 16 + 4 * fq);
;         bf16x8 vf; vf[0] = va[0]; vf[1] = va[1]; vf[2] = va[2]; vf[3] = va[3]; vf[4] = vb[0]; vf[5] = vb[1]; vf[6] = vb[2]; vf[7] = vb[3];
;         vfr[df] = vf;
;       }
;       __builtin_amdgcn_s_setprio(1);
; #pragma unroll
;       for (int df = 0; df < 4; ++df)
; #pragma unroll
;         for (int r = 0; r < 2; ++r) O[df][r] = mfma16(vfr[df], Pf[r], O[df][r]);
;       __builtin_amdgcn_s_setprio(0);
.LBB0_448:
	v_cndmask_b32_e64 v91, v37, v228, s[36:37]
	v_cvt_pk_bf16_f32 v104, v47, v84
	v_cvt_pk_bf16_f32 v105, v85, v46
	v_cvt_pk_bf16_f32 v106, v87, v88
	v_cvt_pk_bf16_f32 v107, v89, v86
	v_sub_f32_e32 v37, v45, v91
	v_sub_f32_e32 v38, v44, v91
	v_sub_f32_e32 v39, v41, v91
	v_sub_f32_e32 v40, v40, v91
	v_sub_f32_e32 v41, v43, v91
	v_sub_f32_e32 v42, v42, v91
	v_sub_f32_e32 v43, v90, v91
	v_sub_f32_e32 v36, v36, v91
	v_exp_f32_e32 v37, v37
	v_exp_f32_e32 v38, v38
	v_exp_f32_e32 v39, v39
	v_exp_f32_e32 v40, v40
	v_exp_f32_e32 v41, v41
	v_exp_f32_e32 v42, v42
	v_exp_f32_e32 v43, v43
	v_exp_f32_e32 v36, v36
	v_cvt_pk_bf16_f32 v116, v37, v38
	v_cvt_pk_bf16_f32 v117, v39, v40
	v_cvt_pk_bf16_f32 v118, v41, v42
	v_cvt_pk_bf16_f32 v119, v43, v36
	s_setprio 1
	s_waitcnt lgkmcnt(3)
	v_mfma_f32_16x16x32_bf16 v[88:91], v[138:141], v[104:107], v[72:75]
	v_mfma_f32_16x16x32_bf16 v[96:99], v[138:141], v[116:119], v[80:83]
	s_waitcnt lgkmcnt(2)
	v_mfma_f32_16x16x32_bf16 v[100:103], v[168:171], v[104:107], v[24:27]
	v_mfma_f32_16x16x32_bf16 v[84:87], v[168:171], v[116:119], v[76:79]
	s_waitcnt lgkmcnt(1)
	v_mfma_f32_16x16x32_bf16 v[92:95], v[108:111], v[104:107], v[20:23]
	v_mfma_f32_16x16x32_bf16 v[76:79], v[108:111], v[116:119], v[32:35]
	s_waitcnt lgkmcnt(0)
	v_mfma_f32_16x16x32_bf16 v[80:83], v[112:115], v[104:107], v[16:19]
	v_mfma_f32_16x16x32_bf16 v[72:75], v[112:115], v[116:119], v[28:31]
	s_setprio 0
	s_xor_b32 s74, s74, 1
	s_cmp_lt_i32 s16, 0
	s_cbranch_scc1 .LBB0_450
	v_mov_b32 v16, v179
	s_lshl_b32 s17, s74, 13
	v_ashrrev_i32_e32 v17, 3, v16
	v_xor_b32_e32 v19, v17, v16
	v_lshl_add_u32 v18, v17, 7, s17
	v_lshlrev_b32_e32 v19, 4, v19
	s_movk_i32 s30, 0x70
	v_lshlrev_b32_e32 v16, 3, v16
	v_and_or_b32 v18, v19, s30, v18
	s_lshl_b32 s30, s74, 9
	v_and_b32_e32 v16, 56, v16
	s_add_i32 s17, s17, s30
	v_mul_u32_u24_e32 v16, 0x88, v16
	v_lshlrev_b32_e32 v17, 1, v17
	v_add3_u32 v16, s17, v16, v17
	s_waitcnt vmcnt(1)
	ds_write_b128 v18, v[56:59]
	s_waitcnt vmcnt(0)
	ds_write_b16 v16, v60 offset:16384
	ds_write_b16_d16_hi v16, v60 offset:16520
	ds_write_b16 v16, v61 offset:16656
	ds_write_b16_d16_hi v16, v61 offset:16792
	ds_write_b16 v16, v62 offset:16928
	ds_write_b16_d16_hi v16, v62 offset:17064
	ds_write_b16 v16, v63 offset:17200
	ds_write_b16_d16_hi v16, v63 offset:17336

; template <int MODE>
; __device__ __forceinline__ void nsa_compute(int cur, int buf, int t, int hl, u64 mymask, const bf16x8 (&Qf)[2][2], f32x4 (&O)[4][2], float (&m)[2], float (&l)[2],
;                                             const float (&inv)[2], float* impw, char* lds) {
;     ...
;   const bool selok = (MODE == 2) ? (((mymask >> cur) & 1ull) != 0ull) : true;
;   const float* tb = (MODE == 3) ? (const float*)(lds + NSA_TW) + hl * 640 : (const float*)(lds + NSA_T) + hl * 4160;
;   constexpr int TS = (MODE == 3) ? 640 : 4160;
;   const int base = (MODE <= 1) ? (t - 31 - 16 * (cur * 64 + 4 * fq) + 64) : (t - cur * 64 - 4 * fq + 64);
; #pragma unroll
;   for (int s2 = 0; s2 < 2; ++s2) {
;     f32x4 S[2][2] = {};
;     bf16x8 kfr[2][2];
; #pragma unroll
;     for (int ks = 0; ks < 2; ++ks)
; #pragma unroll
;       for (int kk = 0; kk < 2; ++kk) kfr[ks][kk] = *(const bf16x8*)(kt + (32 * s2 + 16 * kk + fr) * 128 + (((ks * 4 + fq) ^ (fr & 7)) << 4));
;     __builtin_amdgcn_s_setprio(1);
; #pragma unroll
;     for (int ks = 0; ks < 2; ++ks)
; #pragma unroll
;       for (int kk = 0; kk < 2; ++kk)
; #pragma unroll
;         for (int r = 0; r < 2; ++r) S[kk][r] = mfma16(kfr[ks][kk], Qf[r][ks], S[kk][r]);
;     __builtin_amdgcn_s_setprio(0);
;     bf16x8 Pf[2];
;     float g1s[2] = {0.f, 0.f}, p3s[2] = {0.f, 0.f};
; #pragma unroll
;     for (int r = 0; r < 2; ++r) {
;       float sv[2][4];
; #pragma unroll
;       for (int kk = 0; kk < 2; ++kk)
; #pragma unroll
;         for (int e = 0; e < 4; ++e) {
;           const int off = 32 * s2 + 16 * kk + e;
;           int idx;
;           if (MODE <= 1) { idx = base - 16 * off; idx = idx > 0 ? idx : 0; } else idx = base - off;
;           sv[kk][e] = S[kk][r][e] * (0.125f * LOG2E) + tb[r * TS + idx];
;         }
;       float pv[2][4];
;       if (MODE == 1) {
; #pragma unroll
;         for (int kk = 0; kk < 2; ++kk)
; #pragma unroll
;           for (int e = 0; e < 4; ++e) pv[kk][e] = __builtin_amdgcn_exp2f(sv[kk][e] - m[r]) * inv[r];
; #pragma unroll
;         for (int kk = 0; kk < 2; ++kk) { g1s[kk] += pv[kk][0] + pv[kk][1] + pv[kk][2] + 0.5f * pv[kk][3]; p3s[kk] += 0.5f * pv[kk][3]; }
;       } else {
;         const float mxa = fmaxf(fmaxf(sv[0][0], sv[0][1]), sv[0][2]), mxb = fmaxf(fmaxf(sv[0][3], sv[1][0]), sv[1][1]);
;         float mx = fmaxf(fmaxf(fmaxf(sv[1][2], sv[1][3]), mxa), mxb);
.LBB0_452:
	v_add_f32_e32 v16, 0, v37
	v_add_f32_e32 v16, v38, v16
	v_add_f32_e32 v16, v39, v16
	v_add_f32_e32 v16, v40, v16
	v_add_f32_e32 v16, v41, v16
	v_add_f32_e32 v16, v42, v16
	v_add_f32_e32 v16, v43, v16
	v_add_f32_e32 v16, v36, v16
	s_cmp_lt_i32 s16, 0
	v_add_f32_e32 v145, v145, v16
	s_cbranch_scc1 .LBB0_435
	s_lshl_b64 s[30:31], 1, s16
	v_mov_b32 v18, v179
	v_and_b32_e32 v17, s31, v187
	v_lshrrev_b32_e32 v19, 4, v18
	v_bfe_u32 v24, v18, 4, 2
	v_and_b32_e32 v16, s30, v186
	v_and_b32_e32 v25, 7, v18
	v_and_b32_e32 v117, 15, v18
	s_lshl_b32 s72, s74, 13
	v_cmp_eq_u64_e64 s[36:37], 0, v[16:17]
	v_lshlrev_b32_e32 v118, 2, v24
	v_bitop3_b32 v16, v19, v25, 3 bitop3:0x6c
	v_bitop3_b32 v24, v24, v25, 4 bitop3:0x36
	v_lshlrev_b32_e32 v114, 7, v117
	v_lshl_or_b32 v115, v16, 4, s72
	v_lshl_or_b32 v116, v24, 4, s72
	v_or_b32_e32 v20, v115, v114
	v_or_b32_e32 v28, v116, v114
	ds_read_b128 v[16:19], v20
	ds_read_b128 v[20:23], v20 offset:2048
	ds_read_b128 v[24:27], v28
	ds_read_b128 v[28:31], v28 offset:2048
	v_sub_u32_e32 v251, v180, v118
	v_lshl_add_u32 v251, v251, 2, v181
	s_lshl_b32 s16, s16, 8
	v_subrev_u32_e32 v250, s16, v251
	v_add_u32_e32 v249, 0x8400, v250
	v_add_u32_e32 v248, 0xc500, v250
	ds_read2_b32 v[148:149], v249 offset0:63 offset1:64
	ds_read2_b32 v[150:151], v249 offset0:61 offset1:62
	ds_read2_b32 v[152:153], v249 offset0:47 offset1:48
	ds_read2_b32 v[154:155], v249 offset0:45 offset1:46
	ds_read2_b32 v[156:157], v248 offset0:63 offset1:64
	ds_read2_b32 v[168:169], v248 offset0:61 offset1:62
	ds_read2_b32 v[170:171], v248 offset0:47 offset1:48
	ds_read2_b32 v[172:173], v248 offset0:45 offset1:46
	s_setprio 1
	s_waitcnt lgkmcnt(11)
	v_mfma_f32_16x16x32_bf16 v[32:35], v[16:19], v[0:3], 0
	v_mfma_f32_16x16x32_bf16 v[16:19], v[16:19], v[8:11], 0
	s_waitcnt lgkmcnt(10)
	v_mfma_f32_16x16x32_bf16 v[40:43], v[20:23], v[0:3], 0
	v_mfma_f32_16x16x32_bf16 v[20:23], v[20:23], v[8:11], 0
	s_waitcnt lgkmcnt(9)
	v_mfma_f32_16x16x32_bf16 v[36:39], v[24:27], v[12:15], v[16:19]
	s_waitcnt lgkmcnt(8)
	v_mfma_f32_16x16x32_bf16 v[16:19], v[28:31], v[4:7], v[40:43]
	v_mfma_f32_16x16x32_bf16 v[28:31], v[28:31], v[12:15], v[20:23]
	v_mfma_f32_16x16x32_bf16 v[32:35], v[24:27], v[4:7], v[32:35]
	s_setprio 0
	s_nop 0
	v_sub_u32_e32 v20, v180, v118
	v_lshl_add_u32 v20, v20, 2, v181
	v_subrev_u32_e32 v122, s16, v20
	s_waitcnt lgkmcnt(7)
	s_nop 1
	v_fmamk_f32 v47, v32, 0x3e38aa3b, v149
	v_fmamk_f32 v46, v33, 0x3e38aa3b, v148
	s_waitcnt lgkmcnt(6)
	v_fmamk_f32 v43, v34, 0x3e38aa3b, v151
	v_fmamk_f32 v42, v35, 0x3e38aa3b, v150
	s_waitcnt lgkmcnt(5)
	v_fmamk_f32 v41, v16, 0x3e38aa3b, v153
	v_fmamk_f32 v40, v17, 0x3e38aa3b, v152
	v_max3_f32 v16, v47, v46, v43
	v_max3_f32 v17, v42, v41, v40
	s_waitcnt lgkmcnt(4)
	v_fmamk_f32 v45, v18, 0x3e38aa3b, v155
	v_fmamk_f32 v44, v19, 0x3e38aa3b, v154
	s_lshl_b32 s16, s74, 9
	v_mul_u32_u24_e32 v148, 0x44, v117
	s_add_i32 s73, s72, s16
	v_lshlrev_b32_e32 v149, 1, v148
	v_lshlrev_b32_e32 v150, 1, v118
	v_add3_u32 v151, s73, v149, v150
	v_add_u32_e32 v152, 0x4000, v151
	v_add_u32_e32 v153, 0x4800, v151
	ds_read2_b64 v[192:195], v152 offset1:4
	ds_read2_b64 v[198:201], v153 offset0:16 offset1:20
	v_add_u32_e32 v154, 0x5000, v151
	v_add_u32_e32 v155, 0x5800, v151
	ds_read2_b64 v[202:205], v154 offset0:32 offset1:36
	ds_read2_b64 v[206:209], v155 offset0:48 offset1:52
	v_max_f32_e32 v18, v45, v44
	v_max3_f32 v16, v18, v16, v17
	v_cndmask_b32_e64 v16, v16, v225, s[36:37]
	v_add_f32_e32 v17, 0x41000000, v188
	v_cmp_gt_f32_e32 vcc, v16, v17
	s_cbranch_vccz .LBB0_455
	ds_bpermute_b32 v17, v233, v16
	v_max_f32_e32 v16, v16, v16
	v_mov_b32_e32 v105, v189
	v_mov_b32_e32 v147, v145
	s_waitcnt lgkmcnt(0)
	v_max_f32_e32 v17, v17, v17
	v_max_f32_e32 v16, v16, v17
	ds_bpermute_b32 v17, v234, v16
	s_waitcnt lgkmcnt(0)
	v_max3_f32 v104, v188, v16, v17
	v_sub_f32_e32 v16, v188, v104
	v_exp_f32_e32 v32, v16
	v_mov_b64_e32 v[188:189], v[104:105]
	v_mul_f32_e32 v146, v144, v32
	v_pk_mul_f32 v[26:27], v[90:91], v[32:33] op_sel_hi:[1,0]
	v_pk_mul_f32 v[24:25], v[88:89], v[32:33] op_sel_hi:[1,0]
	v_pk_mul_f32 v[18:19], v[102:103], v[32:33] op_sel_hi:[1,0]
	v_pk_mul_f32 v[16:17], v[100:101], v[32:33] op_sel_hi:[1,0]
	v_pk_mul_f32 v[22:23], v[94:95], v[32:33] op_sel_hi:[1,0]
	v_pk_mul_f32 v[20:21], v[92:93], v[32:33] op_sel_hi:[1,0]
	v_pk_mul_f32 v[34:35], v[82:83], v[32:33] op_sel_hi:[1,0]
	v_pk_mul_f32 v[32:33], v[80:81], v[32:33] op_sel_hi:[1,0]
	s_branch .LBB0_456

; template <int MODE>
; __device__ __forceinline__ void nsa_compute(int cur, int buf, int t, int hl, u64 mymask, const bf16x8 (&Qf)[2][2], f32x4 (&O)[4][2], float (&m)[2], float (&l)[2],
;                                             const float (&inv)[2], float* impw, char* lds) {
;     ...
;       for (int kk = 0; kk < 2; ++kk)
; #pragma unroll
;         for (int e = 0; e < 4; ++e) {
;           const int off = 32 * s2 + 16 * kk + e;
;           int idx;
;           if (MODE <= 1) { idx = base - 16 * off; idx = idx > 0 ? idx : 0; } else idx = base - off;
;           sv[kk][e] = S[kk][r][e] * (0.125f * LOG2E) + tb[r * TS + idx];
;         }
;       float pv[2][4];
;       if (MODE == 1) {
; #pragma unroll
;         for (int kk = 0; kk < 2; ++kk)
; #pragma unroll
;           for (int e = 0; e < 4; ++e) pv[kk][e] = __builtin_amdgcn_exp2f(sv[kk][e] - m[r]) * inv[r];
; #pragma unroll
;         for (int kk = 0; kk < 2; ++kk) { g1s[kk] += pv[kk][0] + pv[kk][1] + pv[kk][2] + 0.5f * pv[kk][3]; p3s[kk] += 0.5f * pv[kk][3]; }
;       } else {
;         const float mxa = fmaxf(fmaxf(sv[0][0], sv[0][1]), sv[0][2]), mxb = fmaxf(fmaxf(sv[0][3], sv[1][0]), sv[1][1]);
;         float mx = fmaxf(fmaxf(fmaxf(sv[1][2], sv[1][3]), mxa), mxb);
;         if (MODE == 2) mx = selok ? mx : -__builtin_inff();
;         if (__any(mx > m[r] + 8.0f)) {
;           mx = fmaxf(mx, __shfl_xor(mx, 16)); mx = fmaxf(mx, __shfl_xor(mx, 32));
;           const float mn = fmaxf(m[r], mx), al = __builtin_amdgcn_exp2f(m[r] - mn);
;           m[r] = mn; l[r] *= al;
;           if (MODE != 0) {
; #pragma unroll
;             for (int df = 0; df < 4; ++df) O[df][r] *= al;
;           }
;         }
;         const float me = (MODE == 2) ? (selok ? m[r] : __builtin_inff()) : m[r];
;         float ps = 0.f;
; #pragma unroll
;         for (int kk = 0; kk < 2; ++kk)
; #pragma unroll
;           for (int e = 0; e < 4; ++e) { pv[kk][e] = __builtin_amdgcn_exp2f(sv[kk][e] - me); ps += pv[kk][e]; }
;         l[r] += ps;
.LBB0_456:
	v_cndmask_b32_e64 v104, v104, v228, s[36:37]
	v_sub_f32_e32 v47, v47, v104
	v_exp_f32_e32 v119, v47
	v_sub_f32_e32 v46, v46, v104
	v_exp_f32_e32 v120, v46
	v_sub_f32_e32 v43, v43, v104
	v_exp_f32_e32 v121, v43
	v_sub_f32_e32 v42, v42, v104
	v_exp_f32_e32 v123, v42
	v_sub_f32_e32 v41, v41, v104
	v_add_f32_e32 v47, 0, v119
	v_exp_f32_e32 v124, v41
	v_sub_f32_e32 v40, v40, v104
	v_add_f32_e32 v46, v120, v47
	v_exp_f32_e32 v125, v40
	v_add_f32_e32 v43, v121, v46
	v_add_f32_e32 v42, v123, v43
	v_add_f32_e32 v41, v124, v42
	v_add_f32_e32 v40, v125, v41
	v_sub_f32_e32 v41, v45, v104
	v_exp_f32_e32 v126, v41
	v_sub_f32_e32 v41, v44, v104
	v_exp_f32_e32 v127, v41
	v_add_f32_e32 v40, v126, v40
	v_add_f32_e32 v40, v127, v40
	v_add_f32_e32 v146, v146, v40
	s_waitcnt lgkmcnt(7)
	v_fmamk_f32 v47, v36, 0x3e38aa3b, v157
	v_fmamk_f32 v46, v37, 0x3e38aa3b, v156
	s_waitcnt lgkmcnt(6)
	v_fmamk_f32 v113, v38, 0x3e38aa3b, v169
	v_fmamk_f32 v112, v39, 0x3e38aa3b, v168
	s_waitcnt lgkmcnt(5)
	v_fmamk_f32 v45, v28, 0x3e38aa3b, v171
	v_fmamk_f32 v44, v29, 0x3e38aa3b, v170
	s_waitcnt lgkmcnt(4)
	v_fmamk_f32 v29, v30, 0x3e38aa3b, v173
	v_fmamk_f32 v28, v31, 0x3e38aa3b, v172
	v_max3_f32 v30, v47, v46, v113
	v_max3_f32 v31, v112, v45, v44
	v_max_f32_e32 v36, v29, v28
	v_max3_f32 v30, v36, v30, v31
	v_cndmask_b32_e64 v30, v30, v225, s[36:37]
	v_add_f32_e32 v31, 0x41000000, v189
	v_cmp_gt_f32_e32 vcc, v30, v31
	s_cbranch_vccz .LBB0_458
	ds_bpermute_b32 v31, v233, v30
	v_max_f32_e32 v30, v30, v30
	s_waitcnt lgkmcnt(0)
	v_max_f32_e32 v31, v31, v31
	v_max_f32_e32 v30, v30, v31
	ds_bpermute_b32 v31, v234, v30
	s_waitcnt lgkmcnt(0)
	v_max3_f32 v30, v189, v30, v31
	v_sub_f32_e32 v31, v189, v30
	v_exp_f32_e32 v108, v31
	v_mov_b32_e32 v189, v30
	v_mul_f32_e32 v147, v147, v108
	v_pk_mul_f32 v[38:39], v[98:99], v[108:109] op_sel_hi:[1,0]
	v_pk_mul_f32 v[36:37], v[96:97], v[108:109] op_sel_hi:[1,0]
	v_pk_mul_f32 v[42:43], v[86:87], v[108:109] op_sel_hi:[1,0]
	v_pk_mul_f32 v[40:41], v[84:85], v[108:109] op_sel_hi:[1,0]
	v_pk_mul_f32 v[106:107], v[78:79], v[108:109] op_sel_hi:[1,0]
	v_pk_mul_f32 v[104:105], v[76:77], v[108:109] op_sel_hi:[1,0]
	v_pk_mul_f32 v[110:111], v[74:75], v[108:109] op_sel_hi:[1,0]
	v_pk_mul_f32 v[108:109], v[72:73], v[108:109] op_sel_hi:[1,0]
	s_branch .LBB0_459

; template <int MODE>
; __device__ __forceinline__ void nsa_compute(int cur, int buf, int t, int hl, u64 mymask, const bf16x8 (&Qf)[2][2], f32x4 (&O)[4][2], float (&m)[2], float (&l)[2],
;                                             const float (&inv)[2], float* impw, char* lds) {
;     ...
; #pragma unroll
;     for (int ks = 0; ks < 2; ++ks)
; #pragma unroll
;       for (int kk = 0; kk < 2; ++kk) kfr[ks][kk] = *(const bf16x8*)(kt + (32 * s2 + 16 * kk + fr) * 128 + (((ks * 4 + fq) ^ (fr & 7)) << 4));
;     __builtin_amdgcn_s_setprio(1);
; #pragma unroll
;     for (int ks = 0; ks < 2; ++ks)
; #pragma unroll
;       for (int kk = 0; kk < 2; ++kk)
; #pragma unroll
;         for (int r = 0; r < 2; ++r) S[kk][r] = mfma16(kfr[ks][kk], Qf[r][ks], S[kk][r]);
;     __builtin_amdgcn_s_setprio(0);
;     bf16x8 Pf[2];
;     float g1s[2] = {0.f, 0.f}, p3s[2] = {0.f, 0.f};
; #pragma unroll
;     for (int r = 0; r < 2; ++r) {
;       float sv[2][4];
; #pragma unroll
;       for (int kk = 0; kk < 2; ++kk)
; #pragma unroll
;         for (int e = 0; e < 4; ++e) {
;     ...
;         const float me = (MODE == 2) ? (selok ? m[r] : __builtin_inff()) : m[r];
;         float ps = 0.f;
; #pragma unroll
;         for (int kk = 0; kk < 2; ++kk)
; #pragma unroll
;           for (int e = 0; e < 4; ++e) { pv[kk][e] = __builtin_amdgcn_exp2f(sv[kk][e] - me); ps += pv[kk][e]; }
;         l[r] += ps;
;       }
;       if (MODE != 0) {
;         const unsigned w0 = pk2(pv[0][0], pv[0][1]), w1 = pk2(pv[0][2], pv[0][3]), w2 = pk2(pv[1][0], pv[1][1]), w3 = pk2(pv[1][2], pv[1][3]);
;         u32x4 pw; pw.x = w0; pw.y = w1; pw.z = w2; pw.w = w3;
;         Pf[r] = __builtin_bit_cast(bf16x8, pw);
;       }
;     }
;     if (MODE != 0) {
;       bf16x8 vfr[4];
; #pragma unroll
;       for (int df = 0; df < 4; ++df) {
;         const bf16x4 va = *(const bf16x4*)(vt + (df * 16 + fr) * 68 + 32 * s2 + 4 * fq);
;         const bf16x4 vb = *(const bf16x4*)(vt + (df * 16 + fr) * 68 + 32 * s2 + 16 + 4 * fq);
;         bf16x8 vf; vf[0] = va[0]; vf[1] = va[1]; vf[2] = va[2]; vf[3] = va[3]; vf[4] = vb[0]; vf[5] = vb[1]; vf[6] = vb[2]; vf[7] = vb[3];
;         vfr[df] = vf;
;       }
;       __builtin_amdgcn_s_setprio(1);
; #pragma unroll
;       for (int df = 0; df < 4; ++df)
; #pragma unroll
;         for (int r = 0; r < 2; ++r) O[df][r] = mfma16(vfr[df], Pf[r], O[df][r]);
;       __builtin_amdgcn_s_setprio(0);
;     }
.LBB0_459:
	v_cndmask_b32_e64 v30, v30, v228, s[36:37]
	v_sub_f32_e32 v31, v47, v30
	v_exp_f32_e32 v31, v31
	v_sub_f32_e32 v46, v46, v30
	v_exp_f32_e32 v46, v46
	v_sub_f32_e32 v113, v113, v30
	v_exp_f32_e32 v113, v113
	v_sub_f32_e32 v112, v112, v30
	v_exp_f32_e32 v112, v112
	v_sub_f32_e32 v45, v45, v30
	v_add_f32_e32 v47, 0, v31
	v_exp_f32_e32 v45, v45
	v_sub_f32_e32 v44, v44, v30
	v_add_f32_e32 v47, v46, v47
	v_exp_f32_e32 v44, v44
	v_sub_f32_e32 v29, v29, v30
	v_add_f32_e32 v47, v113, v47
	v_exp_f32_e32 v29, v29
	v_sub_f32_e32 v28, v28, v30
	v_add_f32_e32 v47, v112, v47
	v_exp_f32_e32 v28, v28
	v_add_f32_e32 v47, v45, v47
	v_add_f32_e32 v47, v44, v47
	v_add_f32_e32 v47, v29, v47
	s_lshl_b32 s16, s74, 9
	v_add_f32_e32 v30, v28, v47
	v_cvt_pk_bf16_f32 v135, v29, v28
	v_mul_u32_u24_e32 v28, 0x44, v117
	s_add_i32 s73, s72, s16
	v_lshlrev_b32_e32 v28, 1, v28
	v_lshlrev_b32_e32 v29, 1, v118
	v_add3_u32 v28, s73, v28, v29
	v_cvt_pk_bf16_f32 v129, v121, v123
	v_cvt_pk_bf16_f32 v130, v124, v125
	v_add_u32_e32 v123, 0x4000, v28
	v_add_u32_e32 v124, 0x4800, v28
	v_cvt_pk_bf16_f32 v128, v119, v120
	v_cvt_pk_bf16_f32 v131, v126, v127
	v_cvt_pk_bf16_f32 v132, v31, v46
	v_cvt_pk_bf16_f32 v134, v45, v44
	v_add_u32_e32 v125, 0x5000, v28
	v_add_u32_e32 v126, 0x5800, v28
	v_add_f32_e32 v147, v147, v30
	v_cvt_pk_bf16_f32 v133, v113, v112
	s_setprio 1
	s_waitcnt lgkmcnt(3)
	v_mfma_f32_16x16x32_bf16 v[28:31], v[192:195], v[128:131], v[24:27]
	v_mfma_f32_16x16x32_bf16 v[44:47], v[192:195], v[132:135], v[36:39]
	s_waitcnt lgkmcnt(2)
	v_mfma_f32_16x16x32_bf16 v[24:27], v[198:201], v[128:131], v[16:19]
	v_mfma_f32_16x16x32_bf16 v[40:43], v[198:201], v[132:135], v[40:43]
	s_waitcnt lgkmcnt(1)
	v_mfma_f32_16x16x32_bf16 v[20:23], v[202:205], v[128:131], v[20:23]
	v_mfma_f32_16x16x32_bf16 v[36:39], v[202:205], v[132:135], v[104:107]
	s_waitcnt lgkmcnt(0)
	v_mfma_f32_16x16x32_bf16 v[16:19], v[206:209], v[128:131], v[32:35]
	v_mfma_f32_16x16x32_bf16 v[32:35], v[206:209], v[132:135], v[108:111]
	s_setprio 0
	s_nop 1
	v_add_u32_e32 v108, v115, v114
	v_add_u32_e32 v116, v116, v114
	ds_read_b128 v[104:107], v108 offset:4096
	ds_read_b128 v[108:111], v108 offset:6144
	ds_read_b128 v[112:115], v116 offset:4096
	ds_read_b128 v[116:119], v116 offset:6144
	v_add_u32_e32 v251, 0x8400, v122
	v_add_u32_e32 v250, 0xc500, v122
	ds_read2_b32 v[152:153], v251 offset0:31 offset1:32
	ds_read2_b32 v[154:155], v251 offset0:29 offset1:30
	ds_read2_b32 v[156:157], v251 offset0:15 offset1:16
	ds_read2_b32 v[168:169], v251 offset0:13 offset1:14
	ds_read2_b32 v[170:171], v250 offset0:31 offset1:32
	ds_read2_b32 v[172:173], v250 offset0:29 offset1:30
	ds_read2_b32 v[174:175], v250 offset0:15 offset1:16
	ds_read2_b32 v[192:193], v250 offset0:13 offset1:14
	s_setprio 1
	s_waitcnt lgkmcnt(11)
	v_mfma_f32_16x16x32_bf16 v[128:131], v[104:107], v[0:3], 0
	v_mfma_f32_16x16x32_bf16 v[104:107], v[104:107], v[8:11], 0
	s_waitcnt lgkmcnt(10)
	v_mfma_f32_16x16x32_bf16 v[136:139], v[108:111], v[8:11], 0
	v_mfma_f32_16x16x32_bf16 v[132:135], v[108:111], v[0:3], 0
	s_waitcnt lgkmcnt(9)
	v_mfma_f32_16x16x32_bf16 v[128:131], v[112:115], v[4:7], v[128:131]
	v_mfma_f32_16x16x32_bf16 v[108:111], v[112:115], v[12:15], v[104:107]
	s_waitcnt lgkmcnt(8)
	v_mfma_f32_16x16x32_bf16 v[104:107], v[116:119], v[12:15], v[136:139]
	v_mfma_f32_16x16x32_bf16 v[132:135], v[116:119], v[4:7], v[132:135]
	s_setprio 0
	s_waitcnt lgkmcnt(7)
	s_nop 1
	v_fmamk_f32 v127, v128, 0x3e38aa3b, v153
	v_fmamk_f32 v116, v129, 0x3e38aa3b, v152
	s_waitcnt lgkmcnt(6)
	v_fmamk_f32 v117, v130, 0x3e38aa3b, v155
	v_fmamk_f32 v114, v131, 0x3e38aa3b, v154
	s_waitcnt lgkmcnt(5)
	v_fmamk_f32 v113, v132, 0x3e38aa3b, v157
	v_fmamk_f32 v112, v133, 0x3e38aa3b, v156
	v_max3_f32 v115, v127, v116, v117
	s_waitcnt lgkmcnt(4)
	v_fmamk_f32 v128, v134, 0x3e38aa3b, v169
	v_fmamk_f32 v118, v135, 0x3e38aa3b, v168
	ds_read2_b64 v[152:155], v123 offset0:8 offset1:12
	ds_read2_b64 v[198:201], v124 offset0:24 offset1:28
	ds_read2_b64 v[202:205], v125 offset0:40 offset1:44
	ds_read2_b64 v[206:209], v126 offset0:56 offset1:60
	v_max3_f32 v119, v114, v113, v112
	v_max_f32_e32 v120, v128, v118
	v_max3_f32 v115, v120, v115, v119
	v_cndmask_b32_e64 v115, v115, v225, s[36:37]
	v_add_f32_e32 v119, 0x41000000, v188
	v_cmp_gt_f32_e32 vcc, v115, v119
	s_cbranch_vccz .LBB0_461
	ds_bpermute_b32 v119, v233, v115
	v_max_f32_e32 v115, v115, v115
	v_mov_b32_e32 v121, v189
	s_waitcnt lgkmcnt(0)
	v_max_f32_e32 v119, v119, v119
	v_max_f32_e32 v115, v115, v119
	ds_bpermute_b32 v119, v234, v115
	s_waitcnt lgkmcnt(0)
	v_max3_f32 v120, v188, v115, v119
	v_sub_f32_e32 v115, v188, v120
	v_exp_f32_e32 v130, v115
	v_mov_b64_e32 v[188:189], v[120:121]
	v_mul_f32_e32 v146, v146, v130
	v_pk_mul_f32 v[30:31], v[30:31], v[130:131] op_sel_hi:[1,0]
	v_pk_mul_f32 v[28:29], v[28:29], v[130:131] op_sel_hi:[1,0]
	v_pk_mul_f32 v[26:27], v[26:27], v[130:131] op_sel_hi:[1,0]
	v_pk_mul_f32 v[24:25], v[24:25], v[130:131] op_sel_hi:[1,0]
	v_pk_mul_f32 v[22:23], v[22:23], v[130:131] op_sel_hi:[1,0]
	v_pk_mul_f32 v[20:21], v[20:21], v[130:131] op_sel_hi:[1,0]
	v_pk_mul_f32 v[18:19], v[18:19], v[130:131] op_sel_hi:[1,0]
	v_pk_mul_f32 v[16:17], v[16:17], v[130:131] op_sel_hi:[1,0]
	s_branch .LBB0_462

; template <int MODE>
; __device__ __forceinline__ void nsa_compute(int cur, int buf, int t, int hl, u64 mymask, const bf16x8 (&Qf)[2][2], f32x4 (&O)[4][2], float (&m)[2], float (&l)[2],
;                                             const float (&inv)[2], float* impw, char* lds) {
;     ...
;       for (int kk = 0; kk < 2; ++kk)
; #pragma unroll
;         for (int e = 0; e < 4; ++e) {
;           const int off = 32 * s2 + 16 * kk + e;
;           int idx;
;           if (MODE <= 1) { idx = base - 16 * off; idx = idx > 0 ? idx : 0; } else idx = base - off;
;           sv[kk][e] = S[kk][r][e] * (0.125f * LOG2E) + tb[r * TS + idx];
;         }
;       float pv[2][4];
;       if (MODE == 1) {
; #pragma unroll
;         for (int kk = 0; kk < 2; ++kk)
; #pragma unroll
;           for (int e = 0; e < 4; ++e) pv[kk][e] = __builtin_amdgcn_exp2f(sv[kk][e] - m[r]) * inv[r];
; #pragma unroll
;         for (int kk = 0; kk < 2; ++kk) { g1s[kk] += pv[kk][0] + pv[kk][1] + pv[kk][2] + 0.5f * pv[kk][3]; p3s[kk] += 0.5f * pv[kk][3]; }
;       } else {
;         const float mxa = fmaxf(fmaxf(sv[0][0], sv[0][1]), sv[0][2]), mxb = fmaxf(fmaxf(sv[0][3], sv[1][0]), sv[1][1]);
;         float mx = fmaxf(fmaxf(fmaxf(sv[1][2], sv[1][3]), mxa), mxb);
;         if (MODE == 2) mx = selok ? mx : -__builtin_inff();
;         if (__any(mx > m[r] + 8.0f)) {
;           mx = fmaxf(mx, __shfl_xor(mx, 16)); mx = fmaxf(mx, __shfl_xor(mx, 32));
;           const float mn = fmaxf(m[r], mx), al = __builtin_amdgcn_exp2f(m[r] - mn);
;           m[r] = mn; l[r] *= al;
;           if (MODE != 0) {
; #pragma unroll
;             for (int df = 0; df < 4; ++df) O[df][r] *= al;
;           }
;         }
;         const float me = (MODE == 2) ? (selok ? m[r] : __builtin_inff()) : m[r];
;         float ps = 0.f;
; #pragma unroll
;         for (int kk = 0; kk < 2; ++kk)
; #pragma unroll
;           for (int e = 0; e < 4; ++e) { pv[kk][e] = __builtin_amdgcn_exp2f(sv[kk][e] - me); ps += pv[kk][e]; }
;         l[r] += ps;
.LBB0_462:
	v_cndmask_b32_e64 v129, v120, v228, s[36:37]
	v_sub_f32_e32 v115, v127, v129
	v_exp_f32_e32 v115, v115
	v_sub_f32_e32 v116, v116, v129
	v_exp_f32_e32 v116, v116
	v_sub_f32_e32 v117, v117, v129
	v_exp_f32_e32 v117, v117
	v_sub_f32_e32 v114, v114, v129
	v_exp_f32_e32 v114, v114
	v_add_f32_e32 v119, 0, v115
	v_add_f32_e32 v119, v116, v119
	v_add_f32_e32 v119, v117, v119
	v_sub_f32_e32 v113, v113, v129
	v_add_f32_e32 v120, v114, v119
	v_exp_f32_e32 v119, v113
	v_sub_f32_e32 v112, v112, v129
	v_add_f32_e32 v113, v119, v120
	v_exp_f32_e32 v120, v112
	s_nop 0
	v_add_f32_e32 v112, v120, v113
	v_sub_f32_e32 v113, v128, v129
	v_exp_f32_e32 v121, v113
	v_sub_f32_e32 v113, v118, v129
	v_exp_f32_e32 v118, v113
	v_add_f32_e32 v112, v121, v112
	v_add_f32_e32 v112, v118, v112
	v_add_f32_e32 v146, v146, v112
	s_waitcnt lgkmcnt(7)
	v_fmamk_f32 v113, v108, 0x3e38aa3b, v171
	v_fmamk_f32 v112, v109, 0x3e38aa3b, v170
	s_waitcnt lgkmcnt(6)
	v_fmamk_f32 v109, v110, 0x3e38aa3b, v173
	v_fmamk_f32 v108, v111, 0x3e38aa3b, v172
	s_waitcnt lgkmcnt(5)
	v_fmamk_f32 v111, v104, 0x3e38aa3b, v175
	v_fmamk_f32 v110, v105, 0x3e38aa3b, v174
	s_waitcnt lgkmcnt(4)
	v_fmamk_f32 v105, v106, 0x3e38aa3b, v193
	v_fmamk_f32 v104, v107, 0x3e38aa3b, v192
	v_max3_f32 v106, v113, v112, v109
	v_max3_f32 v107, v108, v111, v110
	v_max_f32_e32 v122, v105, v104
	v_max3_f32 v106, v122, v106, v107
	v_cndmask_b32_e64 v106, v106, v225, s[36:37]
	v_add_f32_e32 v107, 0x41000000, v189
	v_cmp_gt_f32_e32 vcc, v106, v107
	s_cbranch_vccz .LBB0_464
	ds_bpermute_b32 v107, v233, v106
	v_max_f32_e32 v106, v106, v106
	s_waitcnt lgkmcnt(0)
	v_max_f32_e32 v107, v107, v107
	v_max_f32_e32 v106, v106, v107
	ds_bpermute_b32 v107, v234, v106
	s_waitcnt lgkmcnt(0)
	v_max3_f32 v106, v189, v106, v107
	v_sub_f32_e32 v107, v189, v106
	v_exp_f32_e32 v122, v107
	v_mov_b32_e32 v189, v106
	v_mul_f32_e32 v147, v147, v122
	v_pk_mul_f32 v[46:47], v[46:47], v[122:123] op_sel_hi:[1,0]
	v_pk_mul_f32 v[44:45], v[44:45], v[122:123] op_sel_hi:[1,0]
	v_pk_mul_f32 v[42:43], v[42:43], v[122:123] op_sel_hi:[1,0]
	v_pk_mul_f32 v[40:41], v[40:41], v[122:123] op_sel_hi:[1,0]
	v_pk_mul_f32 v[38:39], v[38:39], v[122:123] op_sel_hi:[1,0]
	v_pk_mul_f32 v[36:37], v[36:37], v[122:123] op_sel_hi:[1,0]
	v_pk_mul_f32 v[34:35], v[34:35], v[122:123] op_sel_hi:[1,0]
	v_pk_mul_f32 v[32:33], v[32:33], v[122:123] op_sel_hi:[1,0]
	s_branch .LBB0_465

; #define TIDX opaque_tid()
; __device__ __forceinline__ unsigned pk2(float lo, float hi) { const f32x2v v = {lo, hi}; const bf16x2v r = __builtin_convertvector(v, bf16x2v); return __builtin_bit_cast(unsigned, r); }
; __device__ __forceinline__ void kv_lwrite(const KVRegs& r, char* lds, int buf) {
;   const int tid = TIDX, row = tid >> 3, cq = tid & 7;
;   char* kt = lds + NSA_KT + buf * 8192 + row * 128;
;   *(u32x4*)(kt + ((cq ^ (row & 7)) << 4)) = r.k0;
;   bf16_t* vt = (bf16_t*)(lds + NSA_VT + buf * 8704) + (cq * 8) * 68 + row;
; #pragma unroll
;   for (int i = 0; i < 4; ++i) { vt[(2 * i) * 68] = (bf16_t)(r.v0[i] & 0xffffu); vt[(2 * i + 1) * 68] = (bf16_t)(r.v0[i] >> 16); }
; }
; template <int MODE>
; __device__ __forceinline__ void nsa_compute(int cur, int buf, int t, int hl, u64 mymask, const bf16x8 (&Qf)[2][2], f32x4 (&O)[4][2], float (&m)[2], float (&l)[2],
;                                             const float (&inv)[2], float* impw, char* lds) {
;     ...
;         const float me = (MODE == 2) ? (selok ? m[r] : __builtin_inff()) : m[r];
;         float ps = 0.f;
; #pragma unroll
;         for (int kk = 0; kk < 2; ++kk)
; #pragma unroll
;           for (int e = 0; e < 4; ++e) { pv[kk][e] = __builtin_amdgcn_exp2f(sv[kk][e] - me); ps += pv[kk][e]; }
;         l[r] += ps;
;       }
;       if (MODE != 0) {
;         const unsigned w0 = pk2(pv[0][0], pv[0][1]), w1 = pk2(pv[0][2], pv[0][3]), w2 = pk2(pv[1][0], pv[1][1]), w3 = pk2(pv[1][2], pv[1][3]);
;         u32x4 pw; pw.x = w0; pw.y = w1; pw.z = w2; pw.w = w3;
;         Pf[r] = __builtin_bit_cast(bf16x8, pw);
;       }
;     }
;     if (MODE != 0) {
;       bf16x8 vfr[4];
; #pragma unroll
;       for (int df = 0; df < 4; ++df) {
;         const bf16x4 va = *(const bf16x4*)(vt + (df * 16 + fr) * 68 + 32 * s2 + 4 * fq);
;         const bf16x4 vb = *(const bf16x4*)(vt + (df * 16 + fr) * 68 + 32 * s2 + 16 + 4 * fq);
;         bf16x8 vf; vf[0] = va[0]; vf[1] = va[1]; vf[2] = va[2]; vf[3] = va[3]; vf[4] = vb[0]; vf[5] = vb[1]; vf[6] = vb[2]; vf[7] = vb[3];
;         vfr[df] = vf;
;       }
;       __builtin_amdgcn_s_setprio(1);
; #pragma unroll
;       for (int df = 0; df < 4; ++df)
; #pragma unroll
;         for (int r = 0; r < 2; ++r) O[df][r] = mfma16(vfr[df], Pf[r], O[df][r]);
;       __builtin_amdgcn_s_setprio(0);
.LBB0_465:
	v_cndmask_b32_e64 v106, v106, v228, s[36:37]
	v_sub_f32_e32 v107, v113, v106
	v_exp_f32_e32 v136, v107
	v_sub_f32_e32 v107, v112, v106
	v_exp_f32_e32 v137, v107
	v_sub_f32_e32 v107, v109, v106
	v_exp_f32_e32 v138, v107
	v_sub_f32_e32 v107, v108, v106
	v_exp_f32_e32 v139, v107
	v_sub_f32_e32 v107, v111, v106
	v_cvt_pk_bf16_f32 v132, v115, v116
	v_cvt_pk_bf16_f32 v133, v117, v114
	v_cvt_pk_bf16_f32 v134, v119, v120
	v_cvt_pk_bf16_f32 v135, v121, v118
	v_exp_f32_e32 v140, v107
	v_sub_f32_e32 v107, v110, v106
	v_sub_f32_e32 v105, v105, v106
	v_sub_f32_e32 v104, v104, v106
	v_exp_f32_e32 v141, v107
	v_exp_f32_e32 v142, v105
	v_exp_f32_e32 v143, v104
	v_cvt_pk_bf16_f32 v148, v136, v137
	v_cvt_pk_bf16_f32 v149, v138, v139
	v_cvt_pk_bf16_f32 v150, v140, v141
	v_cvt_pk_bf16_f32 v151, v142, v143
	s_setprio 1
	s_waitcnt lgkmcnt(3)
	v_mfma_f32_16x16x32_bf16 v[104:107], v[152:155], v[132:135], v[28:31]
	v_mfma_f32_16x16x32_bf16 v[108:111], v[152:155], v[148:151], v[44:47]
	s_waitcnt lgkmcnt(2)
	v_mfma_f32_16x16x32_bf16 v[124:127], v[198:201], v[132:135], v[24:27]
	v_mfma_f32_16x16x32_bf16 v[112:115], v[198:201], v[148:151], v[40:43]
	s_waitcnt lgkmcnt(1)
	v_mfma_f32_16x16x32_bf16 v[128:131], v[202:205], v[132:135], v[20:23]
	v_mfma_f32_16x16x32_bf16 v[116:119], v[202:205], v[148:151], v[36:39]
	s_waitcnt lgkmcnt(0)
	v_mfma_f32_16x16x32_bf16 v[132:135], v[206:209], v[132:135], v[16:19]
	v_mfma_f32_16x16x32_bf16 v[120:123], v[206:209], v[148:151], v[32:35]
	s_setprio 0
	s_cmp_lt_i32 s62, 0
	s_cbranch_scc1 .LBB0_467
	v_mov_b32 v16, v179
	s_nop 0
	v_ashrrev_i32_e32 v17, 3, v16
	v_xor_b32_e32 v19, v17, v16
	v_lshlrev_b32_e32 v16, 3, v16
	v_lshlrev_b32_e32 v19, 4, v19
	v_and_b32_e32 v16, 56, v16
	v_lshlrev_b32_e32 v18, 7, v17
	v_and_b32_e32 v19, 0x70, v19
	v_mul_u32_u24_e32 v16, 0x88, v16
	v_lshlrev_b32_e32 v17, 1, v17
	v_add3_u32 v18, s63, v18, v19
	v_add3_u32 v16, s71, v16, v17
	s_waitcnt vmcnt(1)
	ds_write_b128 v18, v[64:67]
	s_waitcnt vmcnt(0)
	ds_write_b16 v16, v68 offset:16384
	ds_write_b16_d16_hi v16, v68 offset:16520
	ds_write_b16 v16, v69 offset:16656
	ds_write_b16_d16_hi v16, v69 offset:16792
	ds_write_b16 v16, v70 offset:16928
	ds_write_b16_d16_hi v16, v70 offset:17064
	ds_write_b16 v16, v71 offset:17200
	ds_write_b16_d16_hi v16, v71 offset:17336

; template <int MODE>
; __device__ __forceinline__ void nsa_compute(int cur, int buf, int t, int hl, u64 mymask, const bf16x8 (&Qf)[2][2], f32x4 (&O)[4][2], float (&m)[2], float (&l)[2],
;                                             const float (&inv)[2], float* impw, char* lds) {
;     ...
;   const bool selok = (MODE == 2) ? (((mymask >> cur) & 1ull) != 0ull) : true;
;   const float* tb = (MODE == 3) ? (const float*)(lds + NSA_TW) + hl * 640 : (const float*)(lds + NSA_T) + hl * 4160;
;   constexpr int TS = (MODE == 3) ? 640 : 4160;
;   const int base = (MODE <= 1) ? (t - 31 - 16 * (cur * 64 + 4 * fq) + 64) : (t - cur * 64 - 4 * fq + 64);
; #pragma unroll
;   for (int s2 = 0; s2 < 2; ++s2) {
;     f32x4 S[2][2] = {};
;     bf16x8 kfr[2][2];
; #pragma unroll
;     for (int ks = 0; ks < 2; ++ks)
; #pragma unroll
;       for (int kk = 0; kk < 2; ++kk) kfr[ks][kk] = *(const bf16x8*)(kt + (32 * s2 + 16 * kk + fr) * 128 + (((ks * 4 + fq) ^ (fr & 7)) << 4));
;     __builtin_amdgcn_s_setprio(1);
; #pragma unroll
;     for (int ks = 0; ks < 2; ++ks)
; #pragma unroll
;       for (int kk = 0; kk < 2; ++kk)
; #pragma unroll
;         for (int r = 0; r < 2; ++r) S[kk][r] = mfma16(kfr[ks][kk], Qf[r][ks], S[kk][r]);
;     __builtin_amdgcn_s_setprio(0);
;     bf16x8 Pf[2];
;     float g1s[2] = {0.f, 0.f}, p3s[2] = {0.f, 0.f};
; #pragma unroll
;     for (int r = 0; r < 2; ++r) {
;       float sv[2][4];
; #pragma unroll
;       for (int kk = 0; kk < 2; ++kk)
; #pragma unroll
;         for (int e = 0; e < 4; ++e) {
;           const int off = 32 * s2 + 16 * kk + e;
;           int idx;
;           if (MODE <= 1) { idx = base - 16 * off; idx = idx > 0 ? idx : 0; } else idx = base - off;
;           sv[kk][e] = S[kk][r][e] * (0.125f * LOG2E) + tb[r * TS + idx];
;         }
;       float pv[2][4];
;       if (MODE == 1) {
; #pragma unroll
;         for (int kk = 0; kk < 2; ++kk)
; #pragma unroll
;           for (int e = 0; e < 4; ++e) pv[kk][e] = __builtin_amdgcn_exp2f(sv[kk][e] - m[r]) * inv[r];
; #pragma unroll
;         for (int kk = 0; kk < 2; ++kk) { g1s[kk] += pv[kk][0] + pv[kk][1] + pv[kk][2] + 0.5f * pv[kk][3]; p3s[kk] += 0.5f * pv[kk][3]; }
;       } else {
;         const float mxa = fmaxf(fmaxf(sv[0][0], sv[0][1]), sv[0][2]), mxb = fmaxf(fmaxf(sv[0][3], sv[1][0]), sv[1][1]);
;         float mx = fmaxf(fmaxf(fmaxf(sv[1][2], sv[1][3]), mxa), mxb);
.LBB0_469:
	v_add_f32_e32 v16, 0, v136
	v_add_f32_e32 v16, v137, v16
	v_add_f32_e32 v16, v138, v16
	v_add_f32_e32 v16, v139, v16
	v_add_f32_e32 v16, v140, v16
	v_add_f32_e32 v16, v141, v16
	v_add_f32_e32 v16, v142, v16
	v_add_f32_e32 v16, v143, v16
	v_add_f32_e32 v147, v147, v16
	s_mov_b64 s[36:37], -1
	s_cmp_lt_i32 s62, 0
	s_mov_b64 vcc, -1
	s_cbranch_scc1 .LBB0_487
	s_lshl_b64 s[36:37], 1, s62
	v_mov_b32 v18, v179
	v_and_b32_e32 v17, s37, v187
	v_lshrrev_b32_e32 v19, 4, v18
	v_bfe_u32 v24, v18, 4, 2
	v_and_b32_e32 v16, s36, v186
	v_and_b32_e32 v25, 7, v18
	v_and_b32_e32 v150, 15, v18
	v_cmp_eq_u64_e64 s[36:37], 0, v[16:17]
	v_lshlrev_b32_e32 v151, 2, v24
	v_bitop3_b32 v16, v19, v25, 3 bitop3:0x6c
	v_bitop3_b32 v24, v24, v25, 4 bitop3:0x36
	v_lshlrev_b32_e32 v26, 7, v150
	v_lshl_add_u32 v16, v16, 4, s63
	v_lshl_add_u32 v24, v24, 4, s63
	v_add_u32_e32 v148, v16, v26
	v_add_u32_e32 v149, v24, v26
	ds_read_b128 v[16:19], v148
	ds_read_b128 v[20:23], v148 offset:2048
	ds_read_b128 v[24:27], v149
	ds_read_b128 v[32:35], v149 offset:2048
	v_sub_u32_e32 v251, v180, v151
	v_lshl_add_u32 v251, v251, 2, v181
	s_lshl_b32 s16, s62, 8
	v_subrev_u32_e32 v250, s16, v251
	v_add_u32_e32 v249, 0x8400, v250
	v_add_u32_e32 v248, 0xc500, v250
	ds_read2_b32 v[192:193], v249 offset0:63 offset1:64
	ds_read2_b32 v[194:195], v249 offset0:61 offset1:62
	ds_read2_b32 v[198:199], v249 offset0:47 offset1:48
	ds_read2_b32 v[200:201], v249 offset0:45 offset1:46
	ds_read2_b32 v[202:203], v248 offset0:63 offset1:64
	ds_read2_b32 v[204:205], v248 offset0:61 offset1:62
	ds_read2_b32 v[206:207], v248 offset0:47 offset1:48
	ds_read2_b32 v[208:209], v248 offset0:45 offset1:46
	s_setprio 1
	s_waitcnt lgkmcnt(11)
	v_mfma_f32_16x16x32_bf16 v[28:31], v[16:19], v[0:3], 0
	v_mfma_f32_16x16x32_bf16 v[16:19], v[16:19], v[8:11], 0
	s_waitcnt lgkmcnt(10)
	v_mfma_f32_16x16x32_bf16 v[36:39], v[20:23], v[0:3], 0
	v_mfma_f32_16x16x32_bf16 v[20:23], v[20:23], v[8:11], 0
	s_waitcnt lgkmcnt(9)
	v_mfma_f32_16x16x32_bf16 v[40:43], v[24:27], v[4:7], v[28:31]
	v_mfma_f32_16x16x32_bf16 v[28:31], v[24:27], v[12:15], v[16:19]
	s_waitcnt lgkmcnt(8)
	v_mfma_f32_16x16x32_bf16 v[16:19], v[32:35], v[4:7], v[36:39]
	v_mfma_f32_16x16x32_bf16 v[20:23], v[32:35], v[12:15], v[20:23]
	s_setprio 0
	v_sub_u32_e32 v24, v180, v151
	v_lshl_add_u32 v24, v24, 2, v181
	v_subrev_u32_e32 v158, s16, v24
	s_waitcnt lgkmcnt(7)
	v_fmamk_f32 v47, v40, 0x3e38aa3b, v193
	v_fmamk_f32 v46, v41, 0x3e38aa3b, v192
	s_waitcnt lgkmcnt(6)
	v_fmamk_f32 v39, v42, 0x3e38aa3b, v195
	v_fmamk_f32 v38, v43, 0x3e38aa3b, v194
	s_waitcnt lgkmcnt(5)
	v_fmamk_f32 v37, v16, 0x3e38aa3b, v199
	v_fmamk_f32 v36, v17, 0x3e38aa3b, v198
	v_max3_f32 v16, v47, v46, v39
	v_max3_f32 v17, v38, v37, v36
	s_waitcnt lgkmcnt(4)
	v_fmamk_f32 v45, v18, 0x3e38aa3b, v201
	v_fmamk_f32 v44, v19, 0x3e38aa3b, v200
	v_mul_u32_u24_e32 v163, 0x44, v150
	v_lshlrev_b32_e32 v176, 1, v163
	v_lshlrev_b32_e32 v192, 1, v151
	v_add3_u32 v193, s71, v176, v192
	v_add_u32_e32 v194, 0x4000, v193
	v_add_u32_e32 v195, 0x4800, v193
	ds_read2_b64 v[198:201], v194 offset1:4
	ds_read2_b64 v[236:239], v195 offset0:16 offset1:20
	v_add_u32_e32 v210, 0x5000, v193
	v_add_u32_e32 v211, 0x5800, v193
	ds_read2_b64 v[240:243], v210 offset0:32 offset1:36
	ds_read2_b64 v[244:247], v211 offset0:48 offset1:52
	v_max_f32_e32 v18, v45, v44
	v_max3_f32 v16, v18, v16, v17
	v_cndmask_b32_e64 v16, v16, v225, s[36:37]
	v_add_f32_e32 v17, 0x41000000, v188
	v_cmp_gt_f32_e32 vcc, v16, v17
	s_cbranch_vccz .LBB0_472
	ds_bpermute_b32 v17, v233, v16
	v_max_f32_e32 v16, v16, v16
	v_mov_b32_e32 v137, v189
	v_mov_b32_e32 v191, v147
	s_waitcnt lgkmcnt(0)
	v_max_f32_e32 v17, v17, v17
	v_max_f32_e32 v16, v16, v17
	ds_bpermute_b32 v17, v234, v16
	s_waitcnt lgkmcnt(0)
	v_max3_f32 v136, v188, v16, v17
	v_sub_f32_e32 v16, v188, v136
	v_exp_f32_e32 v40, v16
	v_mov_b64_e32 v[188:189], v[136:137]
	v_mul_f32_e32 v190, v146, v40
	v_pk_mul_f32 v[18:19], v[106:107], v[40:41] op_sel_hi:[1,0]
	v_pk_mul_f32 v[16:17], v[104:105], v[40:41] op_sel_hi:[1,0]
	v_pk_mul_f32 v[26:27], v[126:127], v[40:41] op_sel_hi:[1,0]
	v_pk_mul_f32 v[24:25], v[124:125], v[40:41] op_sel_hi:[1,0]
	v_pk_mul_f32 v[34:35], v[130:131], v[40:41] op_sel_hi:[1,0]
	v_pk_mul_f32 v[32:33], v[128:129], v[40:41] op_sel_hi:[1,0]
	v_pk_mul_f32 v[42:43], v[134:135], v[40:41] op_sel_hi:[1,0]
	v_pk_mul_f32 v[40:41], v[132:133], v[40:41] op_sel_hi:[1,0]
	s_branch .LBB0_473

; template <int MODE>
; __device__ __forceinline__ void nsa_compute(int cur, int buf, int t, int hl, u64 mymask, const bf16x8 (&Qf)[2][2], f32x4 (&O)[4][2], float (&m)[2], float (&l)[2],
;                                             const float (&inv)[2], float* impw, char* lds) {
;     ...
;       for (int kk = 0; kk < 2; ++kk)
; #pragma unroll
;         for (int e = 0; e < 4; ++e) {
;           const int off = 32 * s2 + 16 * kk + e;
;           int idx;
;           if (MODE <= 1) { idx = base - 16 * off; idx = idx > 0 ? idx : 0; } else idx = base - off;
;           sv[kk][e] = S[kk][r][e] * (0.125f * LOG2E) + tb[r * TS + idx];
;         }
;       float pv[2][4];
;       if (MODE == 1) {
; #pragma unroll
;         for (int kk = 0; kk < 2; ++kk)
; #pragma unroll
;           for (int e = 0; e < 4; ++e) pv[kk][e] = __builtin_amdgcn_exp2f(sv[kk][e] - m[r]) * inv[r];
; #pragma unroll
;         for (int kk = 0; kk < 2; ++kk) { g1s[kk] += pv[kk][0] + pv[kk][1] + pv[kk][2] + 0.5f * pv[kk][3]; p3s[kk] += 0.5f * pv[kk][3]; }
;       } else {
;         const float mxa = fmaxf(fmaxf(sv[0][0], sv[0][1]), sv[0][2]), mxb = fmaxf(fmaxf(sv[0][3], sv[1][0]), sv[1][1]);
;         float mx = fmaxf(fmaxf(fmaxf(sv[1][2], sv[1][3]), mxa), mxb);
;         if (MODE == 2) mx = selok ? mx : -__builtin_inff();
;         if (__any(mx > m[r] + 8.0f)) {
;           mx = fmaxf(mx, __shfl_xor(mx, 16)); mx = fmaxf(mx, __shfl_xor(mx, 32));
;           const float mn = fmaxf(m[r], mx), al = __builtin_amdgcn_exp2f(m[r] - mn);
;           m[r] = mn; l[r] *= al;
;           if (MODE != 0) {
; #pragma unroll
;             for (int df = 0; df < 4; ++df) O[df][r] *= al;
;           }
;         }
;         const float me = (MODE == 2) ? (selok ? m[r] : __builtin_inff()) : m[r];
;         float ps = 0.f;
; #pragma unroll
;         for (int kk = 0; kk < 2; ++kk)
; #pragma unroll
;           for (int e = 0; e < 4; ++e) { pv[kk][e] = __builtin_amdgcn_exp2f(sv[kk][e] - me); ps += pv[kk][e]; }
;         l[r] += ps;
.LBB0_473:
	v_cndmask_b32_e64 v136, v136, v228, s[36:37]
	v_sub_f32_e32 v47, v47, v136
	v_exp_f32_e32 v152, v47
	v_sub_f32_e32 v46, v46, v136
	v_exp_f32_e32 v153, v46
	v_sub_f32_e32 v39, v39, v136
	v_exp_f32_e32 v154, v39
	v_sub_f32_e32 v38, v38, v136
	v_exp_f32_e32 v155, v38
	v_sub_f32_e32 v37, v37, v136
	v_add_f32_e32 v47, 0, v152
	v_exp_f32_e32 v156, v37
	v_sub_f32_e32 v36, v36, v136
	v_add_f32_e32 v46, v153, v47
	v_exp_f32_e32 v157, v36
	v_add_f32_e32 v39, v154, v46
	v_add_f32_e32 v38, v155, v39
	v_add_f32_e32 v37, v156, v38
	v_add_f32_e32 v36, v157, v37
	v_sub_f32_e32 v37, v45, v136
	v_exp_f32_e32 v159, v37
	v_sub_f32_e32 v37, v44, v136
	v_exp_f32_e32 v160, v37
	v_add_f32_e32 v36, v159, v36
	v_add_f32_e32 v36, v160, v36
	v_add_f32_e32 v190, v190, v36
	s_waitcnt lgkmcnt(7)
	v_fmamk_f32 v139, v28, 0x3e38aa3b, v203
	v_fmamk_f32 v138, v29, 0x3e38aa3b, v202
	s_waitcnt lgkmcnt(6)
	v_fmamk_f32 v141, v30, 0x3e38aa3b, v205
	v_fmamk_f32 v140, v31, 0x3e38aa3b, v204
	s_waitcnt lgkmcnt(5)
	v_fmamk_f32 v137, v20, 0x3e38aa3b, v207
	v_fmamk_f32 v136, v21, 0x3e38aa3b, v206
	v_max3_f32 v20, v139, v138, v141
	v_max3_f32 v21, v140, v137, v136
	s_waitcnt lgkmcnt(4)
	v_fmamk_f32 v143, v22, 0x3e38aa3b, v209
	v_fmamk_f32 v142, v23, 0x3e38aa3b, v208
	v_max_f32_e32 v22, v143, v142
	v_max3_f32 v20, v22, v20, v21
	v_cndmask_b32_e64 v20, v20, v225, s[36:37]
	v_add_f32_e32 v21, 0x41000000, v189
	v_cmp_gt_f32_e32 vcc, v20, v21
	s_cbranch_vccz .LBB0_475
	ds_bpermute_b32 v21, v233, v20
	v_max_f32_e32 v20, v20, v20
	s_waitcnt lgkmcnt(0)
	v_max_f32_e32 v21, v21, v21
	v_max_f32_e32 v20, v20, v21
	ds_bpermute_b32 v21, v234, v20
	s_waitcnt lgkmcnt(0)
	v_max3_f32 v161, v189, v20, v21
	v_sub_f32_e32 v20, v189, v161
	v_exp_f32_e32 v44, v20
	v_mov_b32_e32 v189, v161
	v_mul_f32_e32 v191, v191, v44
	v_pk_mul_f32 v[22:23], v[110:111], v[44:45] op_sel_hi:[1,0]
	v_pk_mul_f32 v[20:21], v[108:109], v[44:45] op_sel_hi:[1,0]
	v_pk_mul_f32 v[30:31], v[114:115], v[44:45] op_sel_hi:[1,0]
	v_pk_mul_f32 v[28:29], v[112:113], v[44:45] op_sel_hi:[1,0]
	v_pk_mul_f32 v[38:39], v[118:119], v[44:45] op_sel_hi:[1,0]
	v_pk_mul_f32 v[36:37], v[116:117], v[44:45] op_sel_hi:[1,0]
	v_pk_mul_f32 v[46:47], v[122:123], v[44:45] op_sel_hi:[1,0]
	v_pk_mul_f32 v[44:45], v[120:121], v[44:45] op_sel_hi:[1,0]
	s_branch .LBB0_476

; template <int MODE>
; __device__ __forceinline__ void nsa_compute(int cur, int buf, int t, int hl, u64 mymask, const bf16x8 (&Qf)[2][2], f32x4 (&O)[4][2], float (&m)[2], float (&l)[2],
;                                             const float (&inv)[2], float* impw, char* lds) {
;     ...
; #pragma unroll
;     for (int ks = 0; ks < 2; ++ks)
; #pragma unroll
;       for (int kk = 0; kk < 2; ++kk) kfr[ks][kk] = *(const bf16x8*)(kt + (32 * s2 + 16 * kk + fr) * 128 + (((ks * 4 + fq) ^ (fr & 7)) << 4));
;     __builtin_amdgcn_s_setprio(1);
; #pragma unroll
;     for (int ks = 0; ks < 2; ++ks)
; #pragma unroll
;       for (int kk = 0; kk < 2; ++kk)
; #pragma unroll
;         for (int r = 0; r < 2; ++r) S[kk][r] = mfma16(kfr[ks][kk], Qf[r][ks], S[kk][r]);
;     __builtin_amdgcn_s_setprio(0);
;     bf16x8 Pf[2];
;     float g1s[2] = {0.f, 0.f}, p3s[2] = {0.f, 0.f};
; #pragma unroll
;     for (int r = 0; r < 2; ++r) {
;       float sv[2][4];
; #pragma unroll
;       for (int kk = 0; kk < 2; ++kk)
; #pragma unroll
;         for (int e = 0; e < 4; ++e) {
;     ...
;         const float me = (MODE == 2) ? (selok ? m[r] : __builtin_inff()) : m[r];
;         float ps = 0.f;
; #pragma unroll
;         for (int kk = 0; kk < 2; ++kk)
; #pragma unroll
;           for (int e = 0; e < 4; ++e) { pv[kk][e] = __builtin_amdgcn_exp2f(sv[kk][e] - me); ps += pv[kk][e]; }
;         l[r] += ps;
;       }
;       if (MODE != 0) {
;         const unsigned w0 = pk2(pv[0][0], pv[0][1]), w1 = pk2(pv[0][2], pv[0][3]), w2 = pk2(pv[1][0], pv[1][1]), w3 = pk2(pv[1][2], pv[1][3]);
;         u32x4 pw; pw.x = w0; pw.y = w1; pw.z = w2; pw.w = w3;
;         Pf[r] = __builtin_bit_cast(bf16x8, pw);
;       }
;     }
;     if (MODE != 0) {
;       bf16x8 vfr[4];
; #pragma unroll
;       for (int df = 0; df < 4; ++df) {
;         const bf16x4 va = *(const bf16x4*)(vt + (df * 16 + fr) * 68 + 32 * s2 + 4 * fq);
;         const bf16x4 vb = *(const bf16x4*)(vt + (df * 16 + fr) * 68 + 32 * s2 + 16 + 4 * fq);
;         bf16x8 vf; vf[0] = va[0]; vf[1] = va[1]; vf[2] = va[2]; vf[3] = va[3]; vf[4] = vb[0]; vf[5] = vb[1]; vf[6] = vb[2]; vf[7] = vb[3];
;         vfr[df] = vf;
;       }
;       __builtin_amdgcn_s_setprio(1);
; #pragma unroll
;       for (int df = 0; df < 4; ++df)
; #pragma unroll
;         for (int r = 0; r < 2; ++r) O[df][r] = mfma16(vfr[df], Pf[r], O[df][r]);
;       __builtin_amdgcn_s_setprio(0);
;     }
.LBB0_476:
	v_cvt_pk_bf16_f32 v152, v152, v153
	v_cvt_pk_bf16_f32 v153, v154, v155
	v_cvt_pk_bf16_f32 v154, v156, v157
	v_cndmask_b32_e64 v156, v161, v228, s[36:37]
	v_sub_f32_e32 v139, v139, v156
	v_exp_f32_e32 v139, v139
	v_sub_f32_e32 v138, v138, v156
	v_exp_f32_e32 v138, v138
	v_sub_f32_e32 v141, v141, v156
	v_exp_f32_e32 v141, v141
	v_sub_f32_e32 v140, v140, v156
	v_exp_f32_e32 v140, v140
	v_sub_f32_e32 v137, v137, v156
	v_cvt_pk_bf16_f32 v155, v159, v160
	v_add_f32_e32 v157, 0, v139
	v_exp_f32_e32 v159, v137
	v_add_f32_e32 v157, v138, v157
	v_add_f32_e32 v157, v141, v157
	v_add_f32_e32 v157, v140, v157
	v_sub_f32_e32 v136, v136, v156
	v_add_f32_e32 v137, v159, v157
	v_exp_f32_e32 v157, v136
	s_nop 0
	v_add_f32_e32 v136, v157, v137
	v_sub_f32_e32 v137, v143, v156
	v_exp_f32_e32 v143, v137
	v_sub_f32_e32 v137, v142, v156
	v_exp_f32_e32 v142, v137
	v_cvt_pk_bf16_f32 v137, v141, v140
	v_mul_u32_u24_e32 v140, 0x44, v150
	v_add_f32_e32 v136, v143, v136
	v_lshlrev_b32_e32 v140, 1, v140
	v_lshlrev_b32_e32 v141, 1, v151
	v_add_f32_e32 v136, v142, v136
	v_add3_u32 v150, s71, v140, v141
	v_add_f32_e32 v191, v191, v136
	v_cvt_pk_bf16_f32 v136, v139, v138
	v_cvt_pk_bf16_f32 v138, v159, v157
	v_add_u32_e32 v159, 0x4000, v150
	v_add_u32_e32 v160, 0x4800, v150
	v_cvt_pk_bf16_f32 v139, v143, v142
	v_add_u32_e32 v161, 0x5000, v150
	v_add_u32_e32 v162, 0x5800, v150
	s_setprio 1
	s_waitcnt lgkmcnt(3)
	v_mfma_f32_16x16x32_bf16 v[16:19], v[198:201], v[152:155], v[16:19]
	v_mfma_f32_16x16x32_bf16 v[20:23], v[198:201], v[136:139], v[20:23]
	s_waitcnt lgkmcnt(2)
	v_mfma_f32_16x16x32_bf16 v[24:27], v[236:239], v[152:155], v[24:27]
	v_mfma_f32_16x16x32_bf16 v[28:31], v[236:239], v[136:139], v[28:31]
	s_waitcnt lgkmcnt(1)
	v_mfma_f32_16x16x32_bf16 v[32:35], v[240:243], v[152:155], v[32:35]
	v_mfma_f32_16x16x32_bf16 v[36:39], v[240:243], v[136:139], v[36:39]
	s_waitcnt lgkmcnt(0)
	v_mfma_f32_16x16x32_bf16 v[40:43], v[244:247], v[152:155], v[40:43]
	v_mfma_f32_16x16x32_bf16 v[44:47], v[244:247], v[136:139], v[44:47]
	s_setprio 0
	ds_read_b128 v[136:139], v148 offset:4096
	ds_read_b128 v[140:143], v148 offset:6144
	ds_read_b128 v[150:153], v149 offset:4096
	ds_read_b128 v[154:157], v149 offset:6144
	v_add_u32_e32 v251, 0x8400, v158
	v_add_u32_e32 v250, 0xc500, v158
	ds_read2_b32 v[192:193], v251 offset0:31 offset1:32
	ds_read2_b32 v[194:195], v251 offset0:29 offset1:30
	ds_read2_b32 v[198:199], v251 offset0:15 offset1:16
	ds_read2_b32 v[200:201], v251 offset0:13 offset1:14
	ds_read2_b32 v[202:203], v250 offset0:31 offset1:32
	ds_read2_b32 v[204:205], v250 offset0:29 offset1:30
	ds_read2_b32 v[206:207], v250 offset0:15 offset1:16
	ds_read2_b32 v[208:209], v250 offset0:13 offset1:14
	s_setprio 1
	s_waitcnt lgkmcnt(11)
	v_mfma_f32_16x16x32_bf16 v[164:167], v[136:139], v[0:3], 0
	v_mfma_f32_16x16x32_bf16 v[136:139], v[136:139], v[8:11], 0
	s_waitcnt lgkmcnt(10)
	v_mfma_f32_16x16x32_bf16 v[172:175], v[140:143], v[8:11], 0
	v_mfma_f32_16x16x32_bf16 v[168:171], v[140:143], v[0:3], 0
	s_waitcnt lgkmcnt(9)
	v_mfma_f32_16x16x32_bf16 v[164:167], v[150:153], v[4:7], v[164:167]
	v_mfma_f32_16x16x32_bf16 v[140:143], v[150:153], v[12:15], v[136:139]
	s_waitcnt lgkmcnt(8)
	v_mfma_f32_16x16x32_bf16 v[136:139], v[154:157], v[12:15], v[172:175]
	v_mfma_f32_16x16x32_bf16 v[168:171], v[154:157], v[4:7], v[168:171]
	s_setprio 0
	s_waitcnt lgkmcnt(7)
	s_nop 1
	v_fmamk_f32 v163, v164, 0x3e38aa3b, v193
	v_fmamk_f32 v152, v165, 0x3e38aa3b, v192
	s_waitcnt lgkmcnt(6)
	v_fmamk_f32 v153, v166, 0x3e38aa3b, v195
	v_fmamk_f32 v150, v167, 0x3e38aa3b, v194
	s_waitcnt lgkmcnt(5)
	v_fmamk_f32 v149, v168, 0x3e38aa3b, v199
	v_fmamk_f32 v148, v169, 0x3e38aa3b, v198
	v_max3_f32 v151, v163, v152, v153
	s_waitcnt lgkmcnt(4)
	v_fmamk_f32 v164, v170, 0x3e38aa3b, v201
	v_fmamk_f32 v154, v171, 0x3e38aa3b, v200
	ds_read2_b64 v[172:175], v159 offset0:8 offset1:12
	ds_read2_b64 v[192:195], v160 offset0:24 offset1:28
	ds_read2_b64 v[198:201], v161 offset0:40 offset1:44
	ds_read2_b64 v[236:239], v162 offset0:56 offset1:60
	v_max3_f32 v155, v150, v149, v148
	v_max_f32_e32 v156, v164, v154
	v_max3_f32 v151, v156, v151, v155
	v_cndmask_b32_e64 v151, v151, v225, s[36:37]
	v_add_f32_e32 v155, 0x41000000, v188
	v_cmp_gt_f32_e32 vcc, v151, v155
	s_cbranch_vccz .LBB0_478
	ds_bpermute_b32 v155, v233, v151
	v_max_f32_e32 v151, v151, v151
	v_mov_b32_e32 v157, v189
	s_waitcnt lgkmcnt(0)
	v_max_f32_e32 v155, v155, v155
	v_max_f32_e32 v151, v151, v155
	ds_bpermute_b32 v155, v234, v151
	s_waitcnt lgkmcnt(0)
	v_max3_f32 v156, v188, v151, v155
	v_sub_f32_e32 v151, v188, v156
	v_exp_f32_e32 v166, v151
	v_mov_b64_e32 v[188:189], v[156:157]
	v_mul_f32_e32 v190, v190, v166
	v_pk_mul_f32 v[18:19], v[18:19], v[166:167] op_sel_hi:[1,0]
	v_pk_mul_f32 v[16:17], v[16:17], v[166:167] op_sel_hi:[1,0]
	v_pk_mul_f32 v[26:27], v[26:27], v[166:167] op_sel_hi:[1,0]
	v_pk_mul_f32 v[24:25], v[24:25], v[166:167] op_sel_hi:[1,0]
	v_pk_mul_f32 v[34:35], v[34:35], v[166:167] op_sel_hi:[1,0]
	v_pk_mul_f32 v[32:33], v[32:33], v[166:167] op_sel_hi:[1,0]
	v_pk_mul_f32 v[42:43], v[42:43], v[166:167] op_sel_hi:[1,0]
	v_pk_mul_f32 v[40:41], v[40:41], v[166:167] op_sel_hi:[1,0]
	s_branch .LBB0_479

; template <int MODE>
; __device__ __forceinline__ void nsa_compute(int cur, int buf, int t, int hl, u64 mymask, const bf16x8 (&Qf)[2][2], f32x4 (&O)[4][2], float (&m)[2], float (&l)[2],
;                                             const float (&inv)[2], float* impw, char* lds) {
;     ...
;       for (int kk = 0; kk < 2; ++kk)
; #pragma unroll
;         for (int e = 0; e < 4; ++e) {
;           const int off = 32 * s2 + 16 * kk + e;
;           int idx;
;           if (MODE <= 1) { idx = base - 16 * off; idx = idx > 0 ? idx : 0; } else idx = base - off;
;           sv[kk][e] = S[kk][r][e] * (0.125f * LOG2E) + tb[r * TS + idx];
;         }
;       float pv[2][4];
;       if (MODE == 1) {
; #pragma unroll
;         for (int kk = 0; kk < 2; ++kk)
; #pragma unroll
;           for (int e = 0; e < 4; ++e) pv[kk][e] = __builtin_amdgcn_exp2f(sv[kk][e] - m[r]) * inv[r];
; #pragma unroll
;         for (int kk = 0; kk < 2; ++kk) { g1s[kk] += pv[kk][0] + pv[kk][1] + pv[kk][2] + 0.5f * pv[kk][3]; p3s[kk] += 0.5f * pv[kk][3]; }
;       } else {
;         const float mxa = fmaxf(fmaxf(sv[0][0], sv[0][1]), sv[0][2]), mxb = fmaxf(fmaxf(sv[0][3], sv[1][0]), sv[1][1]);
;         float mx = fmaxf(fmaxf(fmaxf(sv[1][2], sv[1][3]), mxa), mxb);
;         if (MODE == 2) mx = selok ? mx : -__builtin_inff();
;         if (__any(mx > m[r] + 8.0f)) {
;           mx = fmaxf(mx, __shfl_xor(mx, 16)); mx = fmaxf(mx, __shfl_xor(mx, 32));
;           const float mn = fmaxf(m[r], mx), al = __builtin_amdgcn_exp2f(m[r] - mn);
;           m[r] = mn; l[r] *= al;
;           if (MODE != 0) {
; #pragma unroll
;             for (int df = 0; df < 4; ++df) O[df][r] *= al;
;           }
;         }
;         const float me = (MODE == 2) ? (selok ? m[r] : __builtin_inff()) : m[r];
;         float ps = 0.f;
; #pragma unroll
;         for (int kk = 0; kk < 2; ++kk)
; #pragma unroll
;           for (int e = 0; e < 4; ++e) { pv[kk][e] = __builtin_amdgcn_exp2f(sv[kk][e] - me); ps += pv[kk][e]; }
;         l[r] += ps;
.LBB0_479:
	v_cndmask_b32_e64 v165, v156, v228, s[36:37]
	v_sub_f32_e32 v151, v163, v165
	v_exp_f32_e32 v151, v151
	v_sub_f32_e32 v152, v152, v165
	v_exp_f32_e32 v152, v152
	v_sub_f32_e32 v153, v153, v165
	v_exp_f32_e32 v153, v153
	v_sub_f32_e32 v150, v150, v165
	v_exp_f32_e32 v150, v150
	v_add_f32_e32 v155, 0, v151
	v_add_f32_e32 v155, v152, v155
	v_add_f32_e32 v155, v153, v155
	v_sub_f32_e32 v149, v149, v165
	v_add_f32_e32 v156, v150, v155
	v_exp_f32_e32 v155, v149
	v_sub_f32_e32 v148, v148, v165
	v_add_f32_e32 v149, v155, v156
	v_exp_f32_e32 v156, v148
	s_nop 0
	v_add_f32_e32 v148, v156, v149
	v_sub_f32_e32 v149, v164, v165
	v_exp_f32_e32 v157, v149
	v_sub_f32_e32 v149, v154, v165
	v_exp_f32_e32 v154, v149
	v_add_f32_e32 v148, v157, v148
	v_add_f32_e32 v148, v154, v148
	v_add_f32_e32 v190, v190, v148
	s_waitcnt lgkmcnt(7)
	v_fmamk_f32 v149, v140, 0x3e38aa3b, v203
	v_fmamk_f32 v148, v141, 0x3e38aa3b, v202
	s_waitcnt lgkmcnt(6)
	v_fmamk_f32 v141, v142, 0x3e38aa3b, v205
	v_fmamk_f32 v140, v143, 0x3e38aa3b, v204
	s_waitcnt lgkmcnt(5)
	v_fmamk_f32 v143, v136, 0x3e38aa3b, v207
	v_fmamk_f32 v142, v137, 0x3e38aa3b, v206
	s_waitcnt lgkmcnt(4)
	v_fmamk_f32 v158, v138, 0x3e38aa3b, v209
	v_fmamk_f32 v136, v139, 0x3e38aa3b, v208
	v_max3_f32 v137, v149, v148, v141
	v_max3_f32 v138, v140, v143, v142
	v_max_f32_e32 v139, v158, v136
	v_max3_f32 v137, v139, v137, v138
	v_cndmask_b32_e64 v137, v137, v225, s[36:37]
	v_add_f32_e32 v138, 0x41000000, v189
	v_cmp_gt_f32_e32 vcc, v137, v138
	s_cbranch_vccz .LBB0_481
	ds_bpermute_b32 v138, v233, v137
	v_max_f32_e32 v137, v137, v137
	s_waitcnt lgkmcnt(0)
	v_max_f32_e32 v138, v138, v138
	v_max_f32_e32 v137, v137, v138
	ds_bpermute_b32 v138, v234, v137
	s_waitcnt lgkmcnt(0)
	v_max3_f32 v137, v189, v137, v138
	v_sub_f32_e32 v138, v189, v137
	v_exp_f32_e32 v138, v138
	v_mov_b32_e32 v189, v137
	v_mul_f32_e32 v191, v191, v138
	v_pk_mul_f32 v[22:23], v[22:23], v[138:139] op_sel_hi:[1,0]
	v_pk_mul_f32 v[20:21], v[20:21], v[138:139] op_sel_hi:[1,0]
	v_pk_mul_f32 v[30:31], v[30:31], v[138:139] op_sel_hi:[1,0]
	v_pk_mul_f32 v[28:29], v[28:29], v[138:139] op_sel_hi:[1,0]
	v_pk_mul_f32 v[38:39], v[38:39], v[138:139] op_sel_hi:[1,0]
	v_pk_mul_f32 v[36:37], v[36:37], v[138:139] op_sel_hi:[1,0]
	v_pk_mul_f32 v[46:47], v[46:47], v[138:139] op_sel_hi:[1,0]
	v_pk_mul_f32 v[44:45], v[44:45], v[138:139] op_sel_hi:[1,0]
	s_branch .LBB0_482

; #define TIDX opaque_tid()
; __device__ __forceinline__ unsigned pk2(float lo, float hi) { const f32x2v v = {lo, hi}; const bf16x2v r = __builtin_convertvector(v, bf16x2v); return __builtin_bit_cast(unsigned, r); }
; __device__ __forceinline__ void kv_lwrite(const KVRegs& r, char* lds, int buf) {
;   const int tid = TIDX, row = tid >> 3, cq = tid & 7;
;   char* kt = lds + NSA_KT + buf * 8192 + row * 128;
;   *(u32x4*)(kt + ((cq ^ (row & 7)) << 4)) = r.k0;
;   bf16_t* vt = (bf16_t*)(lds + NSA_VT + buf * 8704) + (cq * 8) * 68 + row;
; #pragma unroll
;   for (int i = 0; i < 4; ++i) { vt[(2 * i) * 68] = (bf16_t)(r.v0[i] & 0xffffu); vt[(2 * i + 1) * 68] = (bf16_t)(r.v0[i] >> 16); }
; }
; template <int MODE>
; __device__ __forceinline__ void nsa_compute(int cur, int buf, int t, int hl, u64 mymask, const bf16x8 (&Qf)[2][2], f32x4 (&O)[4][2], float (&m)[2], float (&l)[2],
;                                             const float (&inv)[2], float* impw, char* lds) {
;     ...
;         const float me = (MODE == 2) ? (selok ? m[r] : __builtin_inff()) : m[r];
;         float ps = 0.f;
; #pragma unroll
;         for (int kk = 0; kk < 2; ++kk)
; #pragma unroll
;           for (int e = 0; e < 4; ++e) { pv[kk][e] = __builtin_amdgcn_exp2f(sv[kk][e] - me); ps += pv[kk][e]; }
;         l[r] += ps;
;       }
;       if (MODE != 0) {
;         const unsigned w0 = pk2(pv[0][0], pv[0][1]), w1 = pk2(pv[0][2], pv[0][3]), w2 = pk2(pv[1][0], pv[1][1]), w3 = pk2(pv[1][2], pv[1][3]);
;         u32x4 pw; pw.x = w0; pw.y = w1; pw.z = w2; pw.w = w3;
;         Pf[r] = __builtin_bit_cast(bf16x8, pw);
;       }
;     }
;     if (MODE != 0) {
;       bf16x8 vfr[4];
; #pragma unroll
;       for (int df = 0; df < 4; ++df) {
;         const bf16x4 va = *(const bf16x4*)(vt + (df * 16 + fr) * 68 + 32 * s2 + 4 * fq);
;         const bf16x4 vb = *(const bf16x4*)(vt + (df * 16 + fr) * 68 + 32 * s2 + 16 + 4 * fq);
;         bf16x8 vf; vf[0] = va[0]; vf[1] = va[1]; vf[2] = va[2]; vf[3] = va[3]; vf[4] = vb[0]; vf[5] = vb[1]; vf[6] = vb[2]; vf[7] = vb[3];
;         vfr[df] = vf;
;       }
;       __builtin_amdgcn_s_setprio(1);
; #pragma unroll
;       for (int df = 0; df < 4; ++df)
; #pragma unroll
;         for (int r = 0; r < 2; ++r) O[df][r] = mfma16(vfr[df], Pf[r], O[df][r]);
;       __builtin_amdgcn_s_setprio(0);
.LBB0_482:
	v_cndmask_b32_e64 v163, v137, v228, s[36:37]
	v_cvt_pk_bf16_f32 v164, v151, v152
	v_cvt_pk_bf16_f32 v165, v153, v150
	v_cvt_pk_bf16_f32 v166, v155, v156
	v_cvt_pk_bf16_f32 v167, v157, v154
	v_sub_f32_e32 v137, v149, v163
	v_sub_f32_e32 v138, v148, v163
	v_sub_f32_e32 v139, v141, v163
	v_sub_f32_e32 v140, v140, v163
	v_sub_f32_e32 v141, v143, v163
	v_sub_f32_e32 v142, v142, v163
	v_sub_f32_e32 v143, v158, v163
	v_sub_f32_e32 v136, v136, v163
	v_exp_f32_e32 v137, v137
	v_exp_f32_e32 v138, v138
	v_exp_f32_e32 v139, v139
	v_exp_f32_e32 v140, v140
	v_exp_f32_e32 v141, v141
	v_exp_f32_e32 v142, v142
	v_exp_f32_e32 v143, v143
	v_exp_f32_e32 v136, v136
	v_cvt_pk_bf16_f32 v168, v137, v138
	v_cvt_pk_bf16_f32 v169, v139, v140
	v_cvt_pk_bf16_f32 v170, v141, v142
	v_cvt_pk_bf16_f32 v171, v143, v136
	s_setprio 1
	s_waitcnt lgkmcnt(3)
	v_mfma_f32_16x16x32_bf16 v[16:19], v[172:175], v[164:167], v[16:19]
	v_mfma_f32_16x16x32_bf16 v[20:23], v[172:175], v[168:171], v[20:23]
	s_waitcnt lgkmcnt(2)
	v_mfma_f32_16x16x32_bf16 v[24:27], v[192:195], v[164:167], v[24:27]
	v_mfma_f32_16x16x32_bf16 v[28:31], v[192:195], v[168:171], v[28:31]
	s_waitcnt lgkmcnt(1)
	v_mfma_f32_16x16x32_bf16 v[32:35], v[198:201], v[164:167], v[32:35]
	v_mfma_f32_16x16x32_bf16 v[36:39], v[198:201], v[168:171], v[36:39]
	s_waitcnt lgkmcnt(0)
	v_mfma_f32_16x16x32_bf16 v[40:43], v[236:239], v[164:167], v[40:43]
	v_mfma_f32_16x16x32_bf16 v[44:47], v[236:239], v[168:171], v[44:47]
	s_setprio 0
	s_cmp_lt_i32 s75, 0
	s_cbranch_scc1 .LBB0_484
	v_mov_b32 v148, v179
	s_nop 0
	v_ashrrev_i32_e32 v149, 3, v148
	v_xor_b32_e32 v151, v149, v148
	v_lshlrev_b32_e32 v148, 3, v148
	v_lshlrev_b32_e32 v151, 4, v151
	v_and_b32_e32 v148, 56, v148
	v_lshlrev_b32_e32 v150, 7, v149
	v_and_b32_e32 v151, 0x70, v151
	v_mul_u32_u24_e32 v148, 0x88, v148
	v_lshlrev_b32_e32 v149, 1, v149
	v_add3_u32 v150, s72, v150, v151
	v_add3_u32 v148, s73, v148, v149
	s_waitcnt vmcnt(1)
	ds_write_b128 v150, v[48:51]
	s_waitcnt vmcnt(0)
	ds_write_b16 v148, v52 offset:16384
	ds_write_b16_d16_hi v148, v52 offset:16520
	ds_write_b16 v148, v53 offset:16656
	ds_write_b16_d16_hi v148, v53 offset:16792
	ds_write_b16 v148, v54 offset:16928
	ds_write_b16_d16_hi v148, v54 offset:17064
	ds_write_b16 v148, v55 offset:17200
	ds_write_b16_d16_hi v148, v55 offset:17336
